# v68 + counted lgkmcnt waits in attention PV groups + merged vmcnt/lgkmcnt wait instruction in GEMM K-loops
# speedup vs baseline: 1.0226x; 1.0034x over previous
.LBB0_173:
	ds_read_b128 v[144:147], v155
	ds_read_b128 v[148:151], v155 offset:1024
	ds_read_b128 v[158:161], v155 offset:2048
	ds_read_b128 v[162:165], v155 offset:3072
	ds_read_b128 v[166:169], v156
	ds_read_b128 v[170:173], v156 offset:1024
	ds_read_b128 v[174:177], v156 offset:2048
	ds_read_b128 v[178:181], v156 offset:3072
	s_add_u32 s68, s66, 0xfff80080
	s_addc_u32 s69, s67, -1
	s_cmp_eq_u32 s77, 28
	s_cselect_b32 s71, s55, s69
	s_cselect_b32 s70, s59, s68
	s_cselect_b32 s69, s57, s76
	s_cselect_b32 s68, s65, s73
	s_add_i32 m0, s25, 0xc000
	ds_read_b128 v[182:185], v157
	ds_read_b128 v[186:189], v157 offset:1024
	ds_read_b128 v[190:193], v157 offset:2048
	ds_read_b128 v[194:197], v157 offset:3072
	ds_read_b128 v[198:201], v157 offset:4096
	ds_read_b128 v[202:205], v157 offset:5120
	ds_read_b128 v[206:209], v157 offset:6144
	ds_read_b128 v[210:213], v157 offset:7168
	global_load_lds_dwordx4 v136, s[66:67]
	s_add_i32 m0, s25, 0xe000
	s_nop 0
	global_load_lds_dwordx4 v138, s[66:67]
	s_waitcnt vmcnt(8) lgkmcnt(0)
	s_setprio 1
	s_barrier
	v_mfma_i32_16x16x64_i8 v[124:127], v[144:147], v[182:185], v[124:127]
	v_mfma_i32_16x16x64_i8 v[116:119], v[158:161], v[182:185], v[116:119]
	v_mfma_i32_16x16x64_i8 v[108:111], v[144:147], v[190:193], v[108:111]
	v_mfma_i32_16x16x64_i8 v[100:103], v[158:161], v[190:193], v[100:103]
	v_mfma_i32_16x16x64_i8 v[92:95], v[144:147], v[198:201], v[92:95]
	v_mfma_i32_16x16x64_i8 v[84:87], v[158:161], v[198:201], v[84:87]
	v_mfma_i32_16x16x64_i8 v[76:79], v[144:147], v[206:209], v[76:79]
	v_mfma_i32_16x16x64_i8 v[68:71], v[158:161], v[206:209], v[68:71]
	v_mfma_i32_16x16x64_i8 v[124:127], v[148:151], v[186:189], v[124:127]
	v_mfma_i32_16x16x64_i8 v[116:119], v[162:165], v[186:189], v[116:119]
	v_mfma_i32_16x16x64_i8 v[108:111], v[148:151], v[194:197], v[108:111]
	v_mfma_i32_16x16x64_i8 v[100:103], v[162:165], v[194:197], v[100:103]
	v_mfma_i32_16x16x64_i8 v[92:95], v[148:151], v[202:205], v[92:95]
	v_mfma_i32_16x16x64_i8 v[84:87], v[162:165], v[202:205], v[84:87]
	v_mfma_i32_16x16x64_i8 v[76:79], v[148:151], v[210:213], v[76:79]
	v_mfma_i32_16x16x64_i8 v[68:71], v[162:165], v[210:213], v[68:71]
	v_mfma_i32_16x16x64_i8 v[120:123], v[166:169], v[182:185], v[120:123]
	v_mfma_i32_16x16x64_i8 v[112:115], v[174:177], v[182:185], v[112:115]
	v_mfma_i32_16x16x64_i8 v[104:107], v[166:169], v[190:193], v[104:107]
	v_mfma_i32_16x16x64_i8 v[96:99], v[174:177], v[190:193], v[96:99]
	v_mfma_i32_16x16x64_i8 v[88:91], v[166:169], v[198:201], v[88:91]
	v_mfma_i32_16x16x64_i8 v[80:83], v[174:177], v[198:201], v[80:83]
	v_mfma_i32_16x16x64_i8 v[72:75], v[166:169], v[206:209], v[72:75]
	v_mfma_i32_16x16x64_i8 v[64:67], v[174:177], v[206:209], v[64:67]
	v_mfma_i32_16x16x64_i8 v[120:123], v[170:173], v[186:189], v[120:123]
	v_mfma_i32_16x16x64_i8 v[112:115], v[178:181], v[186:189], v[112:115]
	v_mfma_i32_16x16x64_i8 v[104:107], v[170:173], v[194:197], v[104:107]
	v_mfma_i32_16x16x64_i8 v[96:99], v[178:181], v[194:197], v[96:99]
	v_mfma_i32_16x16x64_i8 v[88:91], v[170:173], v[202:205], v[88:91]
	v_mfma_i32_16x16x64_i8 v[80:83], v[178:181], v[202:205], v[80:83]
	v_mfma_i32_16x16x64_i8 v[72:75], v[170:173], v[210:213], v[72:75]
	v_mfma_i32_16x16x64_i8 v[64:67], v[178:181], v[210:213], v[64:67]
	s_barrier
	s_setprio 0
	s_add_i32 s78, s35, s13
	s_mov_b32 m0, s78
	ds_read_b128 v[182:185], v157 offset:16384
	ds_read_b128 v[186:189], v157 offset:17408
	ds_read_b128 v[190:193], v157 offset:18432
	ds_read_b128 v[194:197], v157 offset:19456
	ds_read_b128 v[198:201], v157 offset:20480
	ds_read_b128 v[202:205], v157 offset:21504
	ds_read_b128 v[206:209], v157 offset:22528
	ds_read_b128 v[210:213], v157 offset:23552
	global_load_lds_dwordx4 v132, s[68:69]
	s_add_i32 m0, s78, 0x2000
	s_add_u32 s78, s68, 0x80000
	s_mov_b64 s[98:99], s[68:69]
	s_addc_u32 s79, s69, 0
	s_add_i32 s81, s52, s13
	global_load_lds_dwordx4 v128, s[98:99]
	s_mov_b32 m0, s81
	s_mov_b64 s[100:101], s[70:71]
	global_load_lds_dwordx4 v132, s[78:79]
	s_add_i32 m0, s81, 0x2000
	s_nop 0
	global_load_lds_dwordx4 v128, s[78:79]
	s_mov_b64 s[100:101], s[70:71]
	s_mov_b32 m0, s25
	s_nop 0
	global_load_lds_dwordx4 v134, s[100:101]
	s_mov_b32 m0, s26
	s_nop 0
	global_load_lds_dwordx4 v130, s[100:101]
	s_waitcnt vmcnt(8) lgkmcnt(0)
	s_setprio 1
	s_barrier
	v_mfma_i32_16x16x64_i8 v[60:63], v[144:147], v[182:185], v[60:63]
	v_mfma_i32_16x16x64_i8 v[52:55], v[158:161], v[182:185], v[52:55]
	v_mfma_i32_16x16x64_i8 v[44:47], v[144:147], v[190:193], v[44:47]
	v_mfma_i32_16x16x64_i8 v[36:39], v[158:161], v[190:193], v[36:39]
	v_mfma_i32_16x16x64_i8 v[28:31], v[144:147], v[198:201], v[28:31]
	v_mfma_i32_16x16x64_i8 v[20:23], v[158:161], v[198:201], v[20:23]
	v_mfma_i32_16x16x64_i8 v[12:15], v[144:147], v[206:209], v[12:15]
	v_mfma_i32_16x16x64_i8 v[4:7], v[158:161], v[206:209], v[4:7]
	v_mfma_i32_16x16x64_i8 v[60:63], v[148:151], v[186:189], v[60:63]
	v_mfma_i32_16x16x64_i8 v[52:55], v[162:165], v[186:189], v[52:55]
	v_mfma_i32_16x16x64_i8 v[44:47], v[148:151], v[194:197], v[44:47]
	v_mfma_i32_16x16x64_i8 v[36:39], v[162:165], v[194:197], v[36:39]
	v_mfma_i32_16x16x64_i8 v[28:31], v[148:151], v[202:205], v[28:31]
	v_mfma_i32_16x16x64_i8 v[20:23], v[162:165], v[202:205], v[20:23]
	v_mfma_i32_16x16x64_i8 v[12:15], v[148:151], v[210:213], v[12:15]
	v_mfma_i32_16x16x64_i8 v[4:7], v[162:165], v[210:213], v[4:7]
	v_mfma_i32_16x16x64_i8 v[56:59], v[166:169], v[182:185], v[56:59]
	v_mfma_i32_16x16x64_i8 v[48:51], v[174:177], v[182:185], v[48:51]
	v_mfma_i32_16x16x64_i8 v[40:43], v[166:169], v[190:193], v[40:43]
	v_mfma_i32_16x16x64_i8 v[32:35], v[174:177], v[190:193], v[32:35]
	v_mfma_i32_16x16x64_i8 v[24:27], v[166:169], v[198:201], v[24:27]
	v_mfma_i32_16x16x64_i8 v[16:19], v[174:177], v[198:201], v[16:19]
	v_mfma_i32_16x16x64_i8 v[8:11], v[166:169], v[206:209], v[8:11]
	v_mfma_i32_16x16x64_i8 v[0:3], v[174:177], v[206:209], v[0:3]
	v_mfma_i32_16x16x64_i8 v[56:59], v[170:173], v[186:189], v[56:59]
	v_mfma_i32_16x16x64_i8 v[48:51], v[178:181], v[186:189], v[48:51]
	v_mfma_i32_16x16x64_i8 v[40:43], v[170:173], v[194:197], v[40:43]
	v_mfma_i32_16x16x64_i8 v[32:35], v[178:181], v[194:197], v[32:35]
	v_mfma_i32_16x16x64_i8 v[24:27], v[170:173], v[202:205], v[24:27]
	v_mfma_i32_16x16x64_i8 v[16:19], v[178:181], v[202:205], v[16:19]
	v_mfma_i32_16x16x64_i8 v[8:11], v[170:173], v[210:213], v[8:11]
	v_mfma_i32_16x16x64_i8 v[0:3], v[178:181], v[210:213], v[0:3]
	s_barrier
	s_setprio 0
	s_add_i32 s78, 0, 0x18000
	s_add_i32 s79, 0, 0x1c000
	ds_read_b128 v[144:147], v155 offset:32768
	ds_read_b128 v[148:151], v155 offset:33792
	ds_read_b128 v[158:161], v155 offset:34816
	ds_read_b128 v[162:165], v155 offset:35840
	ds_read_b128 v[166:169], v156 offset:32768
	ds_read_b128 v[170:173], v156 offset:33792
	ds_read_b128 v[174:177], v156 offset:34816
	ds_read_b128 v[178:181], v156 offset:35840
	s_add_u32 s70, s70, 0x80000
	s_addc_u32 s71, s71, 0
	s_mov_b32 m0, s27
	ds_read_b128 v[182:185], v157 offset:32768
	ds_read_b128 v[186:189], v157 offset:33792
	ds_read_b128 v[190:193], v157 offset:34816
	ds_read_b128 v[194:197], v157 offset:35840
	ds_read_b128 v[198:201], v157 offset:36864
	ds_read_b128 v[202:205], v157 offset:37888
	ds_read_b128 v[206:209], v157 offset:38912
	ds_read_b128 v[210:213], v157 offset:39936
	global_load_lds_dwordx4 v134, s[70:71]
	s_mov_b32 m0, s28
	s_nop 0
	global_load_lds_dwordx4 v130, s[70:71]
	s_waitcnt vmcnt(8) lgkmcnt(0)
	s_setprio 1
	s_barrier
	v_mfma_i32_16x16x64_i8 v[124:127], v[144:147], v[182:185], v[124:127]
	v_mfma_i32_16x16x64_i8 v[116:119], v[158:161], v[182:185], v[116:119]
	v_mfma_i32_16x16x64_i8 v[108:111], v[144:147], v[190:193], v[108:111]
	v_mfma_i32_16x16x64_i8 v[100:103], v[158:161], v[190:193], v[100:103]
	v_mfma_i32_16x16x64_i8 v[92:95], v[144:147], v[198:201], v[92:95]
	v_mfma_i32_16x16x64_i8 v[84:87], v[158:161], v[198:201], v[84:87]
	v_mfma_i32_16x16x64_i8 v[76:79], v[144:147], v[206:209], v[76:79]
	v_mfma_i32_16x16x64_i8 v[68:71], v[158:161], v[206:209], v[68:71]
	v_mfma_i32_16x16x64_i8 v[124:127], v[148:151], v[186:189], v[124:127]
	v_mfma_i32_16x16x64_i8 v[116:119], v[162:165], v[186:189], v[116:119]
	v_mfma_i32_16x16x64_i8 v[108:111], v[148:151], v[194:197], v[108:111]
	v_mfma_i32_16x16x64_i8 v[100:103], v[162:165], v[194:197], v[100:103]
	v_mfma_i32_16x16x64_i8 v[92:95], v[148:151], v[202:205], v[92:95]
	v_mfma_i32_16x16x64_i8 v[84:87], v[162:165], v[202:205], v[84:87]
	v_mfma_i32_16x16x64_i8 v[76:79], v[148:151], v[210:213], v[76:79]
	v_mfma_i32_16x16x64_i8 v[68:71], v[162:165], v[210:213], v[68:71]
	v_mfma_i32_16x16x64_i8 v[120:123], v[166:169], v[182:185], v[120:123]
	v_mfma_i32_16x16x64_i8 v[112:115], v[174:177], v[182:185], v[112:115]
	v_mfma_i32_16x16x64_i8 v[104:107], v[166:169], v[190:193], v[104:107]
	v_mfma_i32_16x16x64_i8 v[96:99], v[174:177], v[190:193], v[96:99]
	v_mfma_i32_16x16x64_i8 v[88:91], v[166:169], v[198:201], v[88:91]
	v_mfma_i32_16x16x64_i8 v[80:83], v[174:177], v[198:201], v[80:83]
	v_mfma_i32_16x16x64_i8 v[72:75], v[166:169], v[206:209], v[72:75]
	v_mfma_i32_16x16x64_i8 v[64:67], v[174:177], v[206:209], v[64:67]
	v_mfma_i32_16x16x64_i8 v[120:123], v[170:173], v[186:189], v[120:123]
	v_mfma_i32_16x16x64_i8 v[112:115], v[178:181], v[186:189], v[112:115]
	v_mfma_i32_16x16x64_i8 v[104:107], v[170:173], v[194:197], v[104:107]
	v_mfma_i32_16x16x64_i8 v[96:99], v[178:181], v[194:197], v[96:99]
	v_mfma_i32_16x16x64_i8 v[88:91], v[170:173], v[202:205], v[88:91]
	v_mfma_i32_16x16x64_i8 v[80:83], v[178:181], v[202:205], v[80:83]
	v_mfma_i32_16x16x64_i8 v[72:75], v[170:173], v[210:213], v[72:75]
	v_mfma_i32_16x16x64_i8 v[64:67], v[178:181], v[210:213], v[64:67]
	s_barrier
	s_setprio 0
	s_add_i32 s70, s78, s13
	s_add_i32 m0, s70, -128
	ds_read_b128 v[182:185], v157 offset:49152
	ds_read_b128 v[186:189], v157 offset:50176
	ds_read_b128 v[190:193], v157 offset:51200
	ds_read_b128 v[194:197], v157 offset:52224
	ds_read_b128 v[198:201], v157 offset:53248
	ds_read_b128 v[202:205], v157 offset:54272
	ds_read_b128 v[206:209], v157 offset:55296
	ds_read_b128 v[210:213], v157 offset:56320
	global_load_lds_dwordx4 v132, s[68:69] offset:128
	s_add_i32 m0, s70, 8064
	s_add_u32 s68, s68, 0x80080
	s_addc_u32 s69, s69, 0
	s_add_i32 s70, s79, s13
	global_load_lds_dwordx4 v128, s[98:99] offset:128
	s_mov_b32 m0, s70
	s_nop 0
	global_load_lds_dwordx4 v132, s[68:69]
	s_add_i32 m0, s70, 0x2000
	s_nop 0
	global_load_lds_dwordx4 v128, s[68:69]
	s_add_i32 m0, s31, -128
	s_nop 0
	global_load_lds_dwordx4 v134, s[100:101] offset:128
	s_add_i32 m0, s33, -128
	s_nop 0
	global_load_lds_dwordx4 v130, s[100:101] offset:128
	s_waitcnt vmcnt(8) lgkmcnt(0)
	s_setprio 1
	s_barrier
	v_mfma_i32_16x16x64_i8 v[60:63], v[144:147], v[182:185], v[60:63]
	v_mfma_i32_16x16x64_i8 v[52:55], v[158:161], v[182:185], v[52:55]
	v_mfma_i32_16x16x64_i8 v[44:47], v[144:147], v[190:193], v[44:47]
	v_mfma_i32_16x16x64_i8 v[36:39], v[158:161], v[190:193], v[36:39]
	v_mfma_i32_16x16x64_i8 v[28:31], v[144:147], v[198:201], v[28:31]
	v_mfma_i32_16x16x64_i8 v[20:23], v[158:161], v[198:201], v[20:23]
	v_mfma_i32_16x16x64_i8 v[12:15], v[144:147], v[206:209], v[12:15]
	v_mfma_i32_16x16x64_i8 v[4:7], v[158:161], v[206:209], v[4:7]
	v_mfma_i32_16x16x64_i8 v[60:63], v[148:151], v[186:189], v[60:63]
	v_mfma_i32_16x16x64_i8 v[52:55], v[162:165], v[186:189], v[52:55]
	v_mfma_i32_16x16x64_i8 v[44:47], v[148:151], v[194:197], v[44:47]
	v_mfma_i32_16x16x64_i8 v[36:39], v[162:165], v[194:197], v[36:39]
	v_mfma_i32_16x16x64_i8 v[28:31], v[148:151], v[202:205], v[28:31]
	v_mfma_i32_16x16x64_i8 v[20:23], v[162:165], v[202:205], v[20:23]
	v_mfma_i32_16x16x64_i8 v[12:15], v[148:151], v[210:213], v[12:15]
	v_mfma_i32_16x16x64_i8 v[4:7], v[162:165], v[210:213], v[4:7]
	v_mfma_i32_16x16x64_i8 v[56:59], v[166:169], v[182:185], v[56:59]
	v_mfma_i32_16x16x64_i8 v[48:51], v[174:177], v[182:185], v[48:51]
	v_mfma_i32_16x16x64_i8 v[40:43], v[166:169], v[190:193], v[40:43]
	v_mfma_i32_16x16x64_i8 v[32:35], v[174:177], v[190:193], v[32:35]
	v_mfma_i32_16x16x64_i8 v[24:27], v[166:169], v[198:201], v[24:27]
	v_mfma_i32_16x16x64_i8 v[16:19], v[174:177], v[198:201], v[16:19]
	v_mfma_i32_16x16x64_i8 v[8:11], v[166:169], v[206:209], v[8:11]
	v_mfma_i32_16x16x64_i8 v[0:3], v[174:177], v[206:209], v[0:3]
	v_mfma_i32_16x16x64_i8 v[56:59], v[170:173], v[186:189], v[56:59]
	v_mfma_i32_16x16x64_i8 v[48:51], v[178:181], v[186:189], v[48:51]
	v_mfma_i32_16x16x64_i8 v[40:43], v[170:173], v[194:197], v[40:43]
	v_mfma_i32_16x16x64_i8 v[32:35], v[178:181], v[194:197], v[32:35]
	v_mfma_i32_16x16x64_i8 v[24:27], v[170:173], v[202:205], v[24:27]
	v_mfma_i32_16x16x64_i8 v[16:19], v[178:181], v[202:205], v[16:19]
	v_mfma_i32_16x16x64_i8 v[8:11], v[170:173], v[210:213], v[8:11]
	v_mfma_i32_16x16x64_i8 v[0:3], v[178:181], v[210:213], v[0:3]
	s_barrier
	s_setprio 0
	s_add_i32 s77, s77, 2
	s_add_u32 s66, s66, 0x100
	s_addc_u32 s67, s67, 0
	s_add_u32 s73, s73, 0x100
	s_addc_u32 s76, s76, 0
	s_cmp_gt_u32 s77, 29
	s_cbranch_scc0 .LBB0_173
	s_and_b64 vcc, exec, s[20:21]
	s_cbranch_vccz .LBB0_176
	s_barrier

.LBB0_258:
	ds_read_b128 v[152:155], v149
	ds_read_b128 v[156:159], v149 offset:1024
	ds_read_b128 v[160:163], v149 offset:2048
	ds_read_b128 v[164:167], v149 offset:3072
	ds_read_b128 v[168:171], v150
	ds_read_b128 v[172:175], v150 offset:1024
	ds_read_b128 v[176:179], v150 offset:2048
	ds_read_b128 v[180:183], v150 offset:3072
	s_add_u32 s36, s22, 0x100
	s_addc_u32 s37, s23, 0
	s_cmpk_eq_i32 s62, 0xa8
	s_cselect_b32 s57, s5, s37
	s_cselect_b32 s56, s4, s36
	s_cselect_b32 s41, s21, s61
	s_cselect_b32 s40, s20, s60
	s_add_i32 m0, s25, 0xc000
	ds_read_b128 v[184:187], v151
	ds_read_b128 v[188:191], v151 offset:1024
	ds_read_b128 v[192:195], v151 offset:2048
	ds_read_b128 v[196:199], v151 offset:3072
	ds_read_b128 v[200:203], v151 offset:4096
	ds_read_b128 v[204:207], v151 offset:5120
	ds_read_b128 v[208:211], v151 offset:6144
	ds_read_b128 v[212:215], v151 offset:7168
	global_load_lds_dwordx4 v136, s[22:23]
	s_add_i32 m0, s25, 0xe000
	s_nop 0
	global_load_lds_dwordx4 v138, s[22:23]
	s_waitcnt vmcnt(8) lgkmcnt(0)
	s_setprio 1
	s_barrier
	v_mfma_f32_16x16x32_bf16 v[124:127], v[152:155], v[184:187], v[124:127]
	v_mfma_f32_16x16x32_bf16 v[120:123], v[160:163], v[184:187], v[120:123]
	v_mfma_f32_16x16x32_bf16 v[116:119], v[152:155], v[192:195], v[116:119]
	v_mfma_f32_16x16x32_bf16 v[108:111], v[160:163], v[192:195], v[108:111]
	v_mfma_f32_16x16x32_bf16 v[100:103], v[152:155], v[200:203], v[100:103]
	v_mfma_f32_16x16x32_bf16 v[92:95], v[160:163], v[200:203], v[92:95]
	v_mfma_f32_16x16x32_bf16 v[84:87], v[152:155], v[208:211], v[84:87]
	v_mfma_f32_16x16x32_bf16 v[76:79], v[160:163], v[208:211], v[76:79]
	v_mfma_f32_16x16x32_bf16 v[124:127], v[156:159], v[188:191], v[124:127]
	v_mfma_f32_16x16x32_bf16 v[120:123], v[164:167], v[188:191], v[120:123]
	v_mfma_f32_16x16x32_bf16 v[116:119], v[156:159], v[196:199], v[116:119]
	v_mfma_f32_16x16x32_bf16 v[108:111], v[164:167], v[196:199], v[108:111]
	v_mfma_f32_16x16x32_bf16 v[100:103], v[156:159], v[204:207], v[100:103]
	v_mfma_f32_16x16x32_bf16 v[92:95], v[164:167], v[204:207], v[92:95]
	v_mfma_f32_16x16x32_bf16 v[84:87], v[156:159], v[212:215], v[84:87]
	v_mfma_f32_16x16x32_bf16 v[76:79], v[164:167], v[212:215], v[76:79]
	v_mfma_f32_16x16x32_bf16 v[112:115], v[168:171], v[184:187], v[112:115]
	v_mfma_f32_16x16x32_bf16 v[104:107], v[176:179], v[184:187], v[104:107]
	v_mfma_f32_16x16x32_bf16 v[96:99], v[168:171], v[192:195], v[96:99]
	v_mfma_f32_16x16x32_bf16 v[88:91], v[176:179], v[192:195], v[88:91]
	v_mfma_f32_16x16x32_bf16 v[80:83], v[168:171], v[200:203], v[80:83]
	v_mfma_f32_16x16x32_bf16 v[72:75], v[176:179], v[200:203], v[72:75]
	v_mfma_f32_16x16x32_bf16 v[68:71], v[168:171], v[208:211], v[68:71]
	v_mfma_f32_16x16x32_bf16 v[64:67], v[176:179], v[208:211], v[64:67]
	v_mfma_f32_16x16x32_bf16 v[112:115], v[172:175], v[188:191], v[112:115]
	v_mfma_f32_16x16x32_bf16 v[104:107], v[180:183], v[188:191], v[104:107]
	v_mfma_f32_16x16x32_bf16 v[96:99], v[172:175], v[196:199], v[96:99]
	v_mfma_f32_16x16x32_bf16 v[88:91], v[180:183], v[196:199], v[88:91]
	v_mfma_f32_16x16x32_bf16 v[80:83], v[172:175], v[204:207], v[80:83]
	v_mfma_f32_16x16x32_bf16 v[72:75], v[180:183], v[204:207], v[72:75]
	v_mfma_f32_16x16x32_bf16 v[68:71], v[172:175], v[212:215], v[68:71]
	v_mfma_f32_16x16x32_bf16 v[64:67], v[180:183], v[212:215], v[64:67]
	s_barrier
	s_setprio 0
	s_add_i32 s22, s35, s3
	s_mov_b32 m0, s22
	ds_read_b128 v[184:187], v151 offset:16384
	ds_read_b128 v[188:191], v151 offset:17408
	ds_read_b128 v[192:195], v151 offset:18432
	ds_read_b128 v[196:199], v151 offset:19456
	ds_read_b128 v[200:203], v151 offset:20480
	ds_read_b128 v[204:207], v151 offset:21504
	ds_read_b128 v[208:211], v151 offset:22528
	ds_read_b128 v[212:215], v151 offset:23552
	global_load_lds_dwordx4 v132, s[40:41]
	s_add_i32 m0, s22, 0x2000
	s_add_u32 s22, s40, 0x2b0000
	s_mov_b64 s[98:99], s[40:41]
	s_addc_u32 s23, s41, 0
	s_add_i32 s63, s52, s3
	global_load_lds_dwordx4 v128, s[98:99]
	s_mov_b32 m0, s63
	s_nop 0
	global_load_lds_dwordx4 v132, s[22:23]
	s_add_i32 m0, s63, 0x2000
	s_nop 0
	global_load_lds_dwordx4 v128, s[22:23]
	s_mov_b32 m0, s25
	s_nop 0
	global_load_lds_dwordx4 v134, s[56:57]
	s_mov_b32 m0, s26
	s_nop 0
	global_load_lds_dwordx4 v130, s[56:57]
	s_waitcnt vmcnt(8) lgkmcnt(0)
	s_setprio 1
	s_barrier
	v_mfma_f32_16x16x32_bf16 v[60:63], v[152:155], v[184:187], v[60:63]
	v_mfma_f32_16x16x32_bf16 v[56:59], v[160:163], v[184:187], v[56:59]
	v_mfma_f32_16x16x32_bf16 v[52:55], v[152:155], v[192:195], v[52:55]
	v_mfma_f32_16x16x32_bf16 v[44:47], v[160:163], v[192:195], v[44:47]
	v_mfma_f32_16x16x32_bf16 v[36:39], v[152:155], v[200:203], v[36:39]
	v_mfma_f32_16x16x32_bf16 v[28:31], v[160:163], v[200:203], v[28:31]
	v_mfma_f32_16x16x32_bf16 v[20:23], v[152:155], v[208:211], v[20:23]
	v_mfma_f32_16x16x32_bf16 v[12:15], v[160:163], v[208:211], v[12:15]
	v_mfma_f32_16x16x32_bf16 v[60:63], v[156:159], v[188:191], v[60:63]
	v_mfma_f32_16x16x32_bf16 v[56:59], v[164:167], v[188:191], v[56:59]
	v_mfma_f32_16x16x32_bf16 v[52:55], v[156:159], v[196:199], v[52:55]
	v_mfma_f32_16x16x32_bf16 v[44:47], v[164:167], v[196:199], v[44:47]
	v_mfma_f32_16x16x32_bf16 v[36:39], v[156:159], v[204:207], v[36:39]
	v_mfma_f32_16x16x32_bf16 v[28:31], v[164:167], v[204:207], v[28:31]
	v_mfma_f32_16x16x32_bf16 v[20:23], v[156:159], v[212:215], v[20:23]
	v_mfma_f32_16x16x32_bf16 v[12:15], v[164:167], v[212:215], v[12:15]
	v_mfma_f32_16x16x32_bf16 v[48:51], v[168:171], v[184:187], v[48:51]
	v_mfma_f32_16x16x32_bf16 v[40:43], v[176:179], v[184:187], v[40:43]
	v_mfma_f32_16x16x32_bf16 v[32:35], v[168:171], v[192:195], v[32:35]
	v_mfma_f32_16x16x32_bf16 v[24:27], v[176:179], v[192:195], v[24:27]
	v_mfma_f32_16x16x32_bf16 v[16:19], v[168:171], v[200:203], v[16:19]
	v_mfma_f32_16x16x32_bf16 v[8:11], v[176:179], v[200:203], v[8:11]
	v_mfma_f32_16x16x32_bf16 v[4:7], v[168:171], v[208:211], v[4:7]
	v_mfma_f32_16x16x32_bf16 v[0:3], v[176:179], v[208:211], v[0:3]
	v_mfma_f32_16x16x32_bf16 v[48:51], v[172:175], v[188:191], v[48:51]
	v_mfma_f32_16x16x32_bf16 v[40:43], v[180:183], v[188:191], v[40:43]
	v_mfma_f32_16x16x32_bf16 v[32:35], v[172:175], v[196:199], v[32:35]
	v_mfma_f32_16x16x32_bf16 v[24:27], v[180:183], v[196:199], v[24:27]
	v_mfma_f32_16x16x32_bf16 v[16:19], v[172:175], v[204:207], v[16:19]
	v_mfma_f32_16x16x32_bf16 v[8:11], v[180:183], v[204:207], v[8:11]
	v_mfma_f32_16x16x32_bf16 v[4:7], v[172:175], v[212:215], v[4:7]
	v_mfma_f32_16x16x32_bf16 v[0:3], v[180:183], v[212:215], v[0:3]
	s_barrier
	s_setprio 0
	s_add_i32 s63, 0, 0x18000
	s_add_i32 s64, 0, 0x1c000
	ds_read_b128 v[152:155], v149 offset:32768
	ds_read_b128 v[156:159], v149 offset:33792
	ds_read_b128 v[160:163], v149 offset:34816
	ds_read_b128 v[164:167], v149 offset:35840
	ds_read_b128 v[168:171], v150 offset:32768
	ds_read_b128 v[172:175], v150 offset:33792
	ds_read_b128 v[176:179], v150 offset:34816
	ds_read_b128 v[180:183], v150 offset:35840
	s_add_u32 s22, s56, 0x2b0000
	s_addc_u32 s23, s57, 0
	s_mov_b32 m0, s27
	ds_read_b128 v[184:187], v151 offset:32768
	ds_read_b128 v[188:191], v151 offset:33792
	ds_read_b128 v[192:195], v151 offset:34816
	ds_read_b128 v[196:199], v151 offset:35840
	ds_read_b128 v[200:203], v151 offset:36864
	ds_read_b128 v[204:207], v151 offset:37888
	ds_read_b128 v[208:211], v151 offset:38912
	ds_read_b128 v[212:215], v151 offset:39936
	global_load_lds_dwordx4 v134, s[22:23]
	s_mov_b32 m0, s28
	s_nop 0
	global_load_lds_dwordx4 v130, s[22:23]
	s_waitcnt vmcnt(8) lgkmcnt(0)
	s_setprio 1
	s_barrier
	v_mfma_f32_16x16x32_bf16 v[124:127], v[152:155], v[184:187], v[124:127]
	v_mfma_f32_16x16x32_bf16 v[120:123], v[160:163], v[184:187], v[120:123]
	v_mfma_f32_16x16x32_bf16 v[116:119], v[152:155], v[192:195], v[116:119]
	v_mfma_f32_16x16x32_bf16 v[108:111], v[160:163], v[192:195], v[108:111]
	v_mfma_f32_16x16x32_bf16 v[100:103], v[152:155], v[200:203], v[100:103]
	v_mfma_f32_16x16x32_bf16 v[92:95], v[160:163], v[200:203], v[92:95]
	v_mfma_f32_16x16x32_bf16 v[84:87], v[152:155], v[208:211], v[84:87]
	v_mfma_f32_16x16x32_bf16 v[76:79], v[160:163], v[208:211], v[76:79]
	v_mfma_f32_16x16x32_bf16 v[124:127], v[156:159], v[188:191], v[124:127]
	v_mfma_f32_16x16x32_bf16 v[120:123], v[164:167], v[188:191], v[120:123]
	v_mfma_f32_16x16x32_bf16 v[116:119], v[156:159], v[196:199], v[116:119]
	v_mfma_f32_16x16x32_bf16 v[108:111], v[164:167], v[196:199], v[108:111]
	v_mfma_f32_16x16x32_bf16 v[100:103], v[156:159], v[204:207], v[100:103]
	v_mfma_f32_16x16x32_bf16 v[92:95], v[164:167], v[204:207], v[92:95]
	v_mfma_f32_16x16x32_bf16 v[84:87], v[156:159], v[212:215], v[84:87]
	v_mfma_f32_16x16x32_bf16 v[76:79], v[164:167], v[212:215], v[76:79]
	v_mfma_f32_16x16x32_bf16 v[112:115], v[168:171], v[184:187], v[112:115]
	v_mfma_f32_16x16x32_bf16 v[104:107], v[176:179], v[184:187], v[104:107]
	v_mfma_f32_16x16x32_bf16 v[96:99], v[168:171], v[192:195], v[96:99]
	v_mfma_f32_16x16x32_bf16 v[88:91], v[176:179], v[192:195], v[88:91]
	v_mfma_f32_16x16x32_bf16 v[80:83], v[168:171], v[200:203], v[80:83]
	v_mfma_f32_16x16x32_bf16 v[72:75], v[176:179], v[200:203], v[72:75]
	v_mfma_f32_16x16x32_bf16 v[68:71], v[168:171], v[208:211], v[68:71]
	v_mfma_f32_16x16x32_bf16 v[64:67], v[176:179], v[208:211], v[64:67]
	v_mfma_f32_16x16x32_bf16 v[112:115], v[172:175], v[188:191], v[112:115]
	v_mfma_f32_16x16x32_bf16 v[104:107], v[180:183], v[188:191], v[104:107]
	v_mfma_f32_16x16x32_bf16 v[96:99], v[172:175], v[196:199], v[96:99]
	v_mfma_f32_16x16x32_bf16 v[88:91], v[180:183], v[196:199], v[88:91]
	v_mfma_f32_16x16x32_bf16 v[80:83], v[172:175], v[204:207], v[80:83]
	v_mfma_f32_16x16x32_bf16 v[72:75], v[180:183], v[204:207], v[72:75]
	v_mfma_f32_16x16x32_bf16 v[68:71], v[172:175], v[212:215], v[68:71]
	v_mfma_f32_16x16x32_bf16 v[64:67], v[180:183], v[212:215], v[64:67]
	s_barrier
	s_setprio 0
	s_add_i32 s22, s63, s3
	s_add_i32 m0, s22, -128
	ds_read_b128 v[184:187], v151 offset:49152
	ds_read_b128 v[188:191], v151 offset:50176
	ds_read_b128 v[192:195], v151 offset:51200
	ds_read_b128 v[196:199], v151 offset:52224
	ds_read_b128 v[200:203], v151 offset:53248
	ds_read_b128 v[204:207], v151 offset:54272
	ds_read_b128 v[208:211], v151 offset:55296
	ds_read_b128 v[212:215], v151 offset:56320
	global_load_lds_dwordx4 v132, s[40:41] offset:128
	s_add_i32 m0, s22, 8064
	s_add_u32 s22, s40, 0x2b0080
	s_addc_u32 s23, s41, 0
	s_add_i32 s40, s64, s3
	global_load_lds_dwordx4 v128, s[98:99] offset:128
	s_mov_b32 m0, s40
	s_nop 0
	global_load_lds_dwordx4 v132, s[22:23]
	s_add_i32 m0, s40, 0x2000
	s_nop 0
	global_load_lds_dwordx4 v128, s[22:23]
	s_add_i32 m0, s31, -128
	s_nop 0
	global_load_lds_dwordx4 v134, s[56:57] offset:128
	s_add_i32 m0, s33, -128
	s_nop 0
	global_load_lds_dwordx4 v130, s[56:57] offset:128
	s_waitcnt vmcnt(8) lgkmcnt(0)
	s_setprio 1
	s_barrier
	v_mfma_f32_16x16x32_bf16 v[60:63], v[152:155], v[184:187], v[60:63]
	v_mfma_f32_16x16x32_bf16 v[56:59], v[160:163], v[184:187], v[56:59]
	v_mfma_f32_16x16x32_bf16 v[52:55], v[152:155], v[192:195], v[52:55]
	v_mfma_f32_16x16x32_bf16 v[44:47], v[160:163], v[192:195], v[44:47]
	v_mfma_f32_16x16x32_bf16 v[36:39], v[152:155], v[200:203], v[36:39]
	v_mfma_f32_16x16x32_bf16 v[28:31], v[160:163], v[200:203], v[28:31]
	v_mfma_f32_16x16x32_bf16 v[20:23], v[152:155], v[208:211], v[20:23]
	v_mfma_f32_16x16x32_bf16 v[12:15], v[160:163], v[208:211], v[12:15]
	v_mfma_f32_16x16x32_bf16 v[60:63], v[156:159], v[188:191], v[60:63]
	v_mfma_f32_16x16x32_bf16 v[56:59], v[164:167], v[188:191], v[56:59]
	v_mfma_f32_16x16x32_bf16 v[52:55], v[156:159], v[196:199], v[52:55]
	v_mfma_f32_16x16x32_bf16 v[44:47], v[164:167], v[196:199], v[44:47]
	v_mfma_f32_16x16x32_bf16 v[36:39], v[156:159], v[204:207], v[36:39]
	v_mfma_f32_16x16x32_bf16 v[28:31], v[164:167], v[204:207], v[28:31]
	v_mfma_f32_16x16x32_bf16 v[20:23], v[156:159], v[212:215], v[20:23]
	v_mfma_f32_16x16x32_bf16 v[12:15], v[164:167], v[212:215], v[12:15]
	v_mfma_f32_16x16x32_bf16 v[48:51], v[168:171], v[184:187], v[48:51]
	v_mfma_f32_16x16x32_bf16 v[40:43], v[176:179], v[184:187], v[40:43]
	v_mfma_f32_16x16x32_bf16 v[32:35], v[168:171], v[192:195], v[32:35]
	v_mfma_f32_16x16x32_bf16 v[24:27], v[176:179], v[192:195], v[24:27]
	v_mfma_f32_16x16x32_bf16 v[16:19], v[168:171], v[200:203], v[16:19]
	v_mfma_f32_16x16x32_bf16 v[8:11], v[176:179], v[200:203], v[8:11]
	v_mfma_f32_16x16x32_bf16 v[4:7], v[168:171], v[208:211], v[4:7]
	v_mfma_f32_16x16x32_bf16 v[0:3], v[176:179], v[208:211], v[0:3]
	v_mfma_f32_16x16x32_bf16 v[48:51], v[172:175], v[188:191], v[48:51]
	v_mfma_f32_16x16x32_bf16 v[40:43], v[180:183], v[188:191], v[40:43]
	v_mfma_f32_16x16x32_bf16 v[32:35], v[172:175], v[196:199], v[32:35]
	v_mfma_f32_16x16x32_bf16 v[24:27], v[180:183], v[196:199], v[24:27]
	v_mfma_f32_16x16x32_bf16 v[16:19], v[172:175], v[204:207], v[16:19]
	v_mfma_f32_16x16x32_bf16 v[8:11], v[180:183], v[204:207], v[8:11]
	v_mfma_f32_16x16x32_bf16 v[4:7], v[172:175], v[212:215], v[4:7]
	v_mfma_f32_16x16x32_bf16 v[0:3], v[180:183], v[212:215], v[0:3]
	s_barrier
	s_setprio 0
	s_add_i32 s62, s62, 2
	s_add_u32 s60, s60, 0x100
	s_addc_u32 s61, s61, 0
	s_cmpk_gt_u32 s62, 0xa9
	s_mov_b64 s[22:23], s[36:37]
	s_cbranch_scc0 .LBB0_258
	s_and_b64 vcc, exec, s[14:15]
	s_cbranch_vccz .LBB0_261
	s_barrier

.LBB0_394:
	ds_read_b128 v[156:159], v152
	ds_read_b128 v[160:163], v152 offset:1024
	ds_read_b128 v[164:167], v152 offset:2048
	ds_read_b128 v[168:171], v152 offset:3072
	ds_read_b128 v[172:175], v153
	ds_read_b128 v[176:179], v153 offset:1024
	ds_read_b128 v[180:183], v153 offset:2048
	ds_read_b128 v[184:187], v153 offset:3072
	s_add_u32 s40, s38, 0xfff00080
	s_addc_u32 s41, s39, -1
	s_cmp_eq_u32 s64, 60
	s_cselect_b32 s57, s21, s41
	s_cselect_b32 s56, s60, s40
	s_cselect_b32 s41, s15, s63
	s_cselect_b32 s40, s61, s62
	s_add_i32 m0, s29, 0xc000
	ds_read_b128 v[188:191], v154
	ds_read_b128 v[192:195], v154 offset:1024
	ds_read_b128 v[196:199], v154 offset:2048
	ds_read_b128 v[200:203], v154 offset:3072
	ds_read_b128 v[204:207], v154 offset:4096
	ds_read_b128 v[208:211], v154 offset:5120
	ds_read_b128 v[212:215], v154 offset:6144
	ds_read_b128 v[216:219], v154 offset:7168
	global_load_lds_dwordx4 v140, s[38:39]
	s_add_i32 m0, s29, 0xe000
	s_nop 0
	global_load_lds_dwordx4 v142, s[38:39]
	s_waitcnt vmcnt(8) lgkmcnt(0)
	s_setprio 1
	s_barrier
	v_mfma_f32_16x16x32_bf16 v[124:127], v[156:159], v[188:191], v[124:127]
	v_mfma_f32_16x16x32_bf16 v[120:123], v[164:167], v[188:191], v[120:123]
	v_mfma_f32_16x16x32_bf16 v[112:115], v[156:159], v[196:199], v[112:115]
	v_mfma_f32_16x16x32_bf16 v[104:107], v[164:167], v[196:199], v[104:107]
	v_mfma_f32_16x16x32_bf16 v[96:99], v[156:159], v[204:207], v[96:99]
	v_mfma_f32_16x16x32_bf16 v[88:91], v[164:167], v[204:207], v[88:91]
	v_mfma_f32_16x16x32_bf16 v[80:83], v[156:159], v[212:215], v[80:83]
	v_mfma_f32_16x16x32_bf16 v[72:75], v[164:167], v[212:215], v[72:75]
	v_mfma_f32_16x16x32_bf16 v[124:127], v[160:163], v[192:195], v[124:127]
	v_mfma_f32_16x16x32_bf16 v[120:123], v[168:171], v[192:195], v[120:123]
	v_mfma_f32_16x16x32_bf16 v[112:115], v[160:163], v[200:203], v[112:115]
	v_mfma_f32_16x16x32_bf16 v[104:107], v[168:171], v[200:203], v[104:107]
	v_mfma_f32_16x16x32_bf16 v[96:99], v[160:163], v[208:211], v[96:99]
	v_mfma_f32_16x16x32_bf16 v[88:91], v[168:171], v[208:211], v[88:91]
	v_mfma_f32_16x16x32_bf16 v[80:83], v[160:163], v[216:219], v[80:83]
	v_mfma_f32_16x16x32_bf16 v[72:75], v[168:171], v[216:219], v[72:75]
	v_mfma_f32_16x16x32_bf16 v[116:119], v[172:175], v[188:191], v[116:119]
	v_mfma_f32_16x16x32_bf16 v[108:111], v[180:183], v[188:191], v[108:111]
	v_mfma_f32_16x16x32_bf16 v[100:103], v[172:175], v[196:199], v[100:103]
	v_mfma_f32_16x16x32_bf16 v[92:95], v[180:183], v[196:199], v[92:95]
	v_mfma_f32_16x16x32_bf16 v[84:87], v[172:175], v[204:207], v[84:87]
	v_mfma_f32_16x16x32_bf16 v[76:79], v[180:183], v[204:207], v[76:79]
	v_mfma_f32_16x16x32_bf16 v[68:71], v[172:175], v[212:215], v[68:71]
	v_mfma_f32_16x16x32_bf16 v[64:67], v[180:183], v[212:215], v[64:67]
	v_mfma_f32_16x16x32_bf16 v[116:119], v[176:179], v[192:195], v[116:119]
	v_mfma_f32_16x16x32_bf16 v[108:111], v[184:187], v[192:195], v[108:111]
	v_mfma_f32_16x16x32_bf16 v[100:103], v[176:179], v[200:203], v[100:103]
	v_mfma_f32_16x16x32_bf16 v[92:95], v[184:187], v[200:203], v[92:95]
	v_mfma_f32_16x16x32_bf16 v[84:87], v[176:179], v[208:211], v[84:87]
	v_mfma_f32_16x16x32_bf16 v[76:79], v[184:187], v[208:211], v[76:79]
	v_mfma_f32_16x16x32_bf16 v[68:71], v[176:179], v[216:219], v[68:71]
	v_mfma_f32_16x16x32_bf16 v[64:67], v[184:187], v[216:219], v[64:67]
	s_barrier
	s_setprio 0
	s_add_i32 s65, s58, s24
	s_mov_b32 m0, s65
	ds_read_b128 v[188:191], v154 offset:16384
	ds_read_b128 v[192:195], v154 offset:17408
	ds_read_b128 v[196:199], v154 offset:18432
	ds_read_b128 v[200:203], v154 offset:19456
	ds_read_b128 v[204:207], v154 offset:20480
	ds_read_b128 v[208:211], v154 offset:21504
	ds_read_b128 v[212:215], v154 offset:22528
	ds_read_b128 v[216:219], v154 offset:23552
	global_load_lds_dwordx4 v132, s[40:41]
	s_add_i32 m0, s65, 0x2000
	s_add_u32 s66, s40, 0x100000
	s_mov_b64 s[98:99], s[40:41]
	s_addc_u32 s67, s41, 0
	s_add_i32 s65, s59, s24
	global_load_lds_dwordx4 v128, s[98:99]
	s_mov_b32 m0, s65
	s_mov_b64 s[100:101], s[56:57]
	global_load_lds_dwordx4 v132, s[66:67]
	s_add_i32 m0, s65, 0x2000
	s_nop 0
	global_load_lds_dwordx4 v128, s[66:67]
	s_mov_b64 s[100:101], s[56:57]
	s_mov_b32 m0, s29
	s_nop 0
	global_load_lds_dwordx4 v134, s[100:101]
	s_mov_b32 m0, s30
	s_nop 0
	global_load_lds_dwordx4 v130, s[100:101]
	s_waitcnt vmcnt(8) lgkmcnt(0)
	s_setprio 1
	s_barrier
	v_mfma_f32_16x16x32_bf16 v[60:63], v[156:159], v[188:191], v[60:63]
	v_mfma_f32_16x16x32_bf16 v[56:59], v[164:167], v[188:191], v[56:59]
	v_mfma_f32_16x16x32_bf16 v[52:55], v[156:159], v[196:199], v[52:55]
	v_mfma_f32_16x16x32_bf16 v[44:47], v[164:167], v[196:199], v[44:47]
	v_mfma_f32_16x16x32_bf16 v[36:39], v[156:159], v[204:207], v[36:39]
	v_mfma_f32_16x16x32_bf16 v[28:31], v[164:167], v[204:207], v[28:31]
	v_mfma_f32_16x16x32_bf16 v[20:23], v[156:159], v[212:215], v[20:23]
	v_mfma_f32_16x16x32_bf16 v[12:15], v[164:167], v[212:215], v[12:15]
	v_mfma_f32_16x16x32_bf16 v[60:63], v[160:163], v[192:195], v[60:63]
	v_mfma_f32_16x16x32_bf16 v[56:59], v[168:171], v[192:195], v[56:59]
	v_mfma_f32_16x16x32_bf16 v[52:55], v[160:163], v[200:203], v[52:55]
	v_mfma_f32_16x16x32_bf16 v[44:47], v[168:171], v[200:203], v[44:47]
	v_mfma_f32_16x16x32_bf16 v[36:39], v[160:163], v[208:211], v[36:39]
	v_mfma_f32_16x16x32_bf16 v[28:31], v[168:171], v[208:211], v[28:31]
	v_mfma_f32_16x16x32_bf16 v[20:23], v[160:163], v[216:219], v[20:23]
	v_mfma_f32_16x16x32_bf16 v[12:15], v[168:171], v[216:219], v[12:15]
	v_mfma_f32_16x16x32_bf16 v[48:51], v[172:175], v[188:191], v[48:51]
	v_mfma_f32_16x16x32_bf16 v[40:43], v[180:183], v[188:191], v[40:43]
	v_mfma_f32_16x16x32_bf16 v[32:35], v[172:175], v[196:199], v[32:35]
	v_mfma_f32_16x16x32_bf16 v[24:27], v[180:183], v[196:199], v[24:27]
	v_mfma_f32_16x16x32_bf16 v[16:19], v[172:175], v[204:207], v[16:19]
	v_mfma_f32_16x16x32_bf16 v[8:11], v[180:183], v[204:207], v[8:11]
	v_mfma_f32_16x16x32_bf16 v[4:7], v[172:175], v[212:215], v[4:7]
	v_mfma_f32_16x16x32_bf16 v[0:3], v[180:183], v[212:215], v[0:3]
	v_mfma_f32_16x16x32_bf16 v[48:51], v[176:179], v[192:195], v[48:51]
	v_mfma_f32_16x16x32_bf16 v[40:43], v[184:187], v[192:195], v[40:43]
	v_mfma_f32_16x16x32_bf16 v[32:35], v[176:179], v[200:203], v[32:35]
	v_mfma_f32_16x16x32_bf16 v[24:27], v[184:187], v[200:203], v[24:27]
	v_mfma_f32_16x16x32_bf16 v[16:19], v[176:179], v[208:211], v[16:19]
	v_mfma_f32_16x16x32_bf16 v[8:11], v[184:187], v[208:211], v[8:11]
	v_mfma_f32_16x16x32_bf16 v[4:7], v[176:179], v[216:219], v[4:7]
	v_mfma_f32_16x16x32_bf16 v[0:3], v[184:187], v[216:219], v[0:3]
	s_barrier
	s_setprio 0
	s_add_i32 s65, 0, 0x18000
	s_add_i32 s66, 0, 0x1c000
	ds_read_b128 v[156:159], v152 offset:32768
	ds_read_b128 v[160:163], v152 offset:33792
	ds_read_b128 v[164:167], v152 offset:34816
	ds_read_b128 v[168:171], v152 offset:35840
	ds_read_b128 v[172:175], v153 offset:32768
	ds_read_b128 v[176:179], v153 offset:33792
	ds_read_b128 v[180:183], v153 offset:34816
	ds_read_b128 v[184:187], v153 offset:35840
	s_add_u32 s56, s56, 0x100000
	s_addc_u32 s57, s57, 0
	s_mov_b32 m0, s31
	ds_read_b128 v[188:191], v154 offset:32768
	ds_read_b128 v[192:195], v154 offset:33792
	ds_read_b128 v[196:199], v154 offset:34816
	ds_read_b128 v[200:203], v154 offset:35840
	ds_read_b128 v[204:207], v154 offset:36864
	ds_read_b128 v[208:211], v154 offset:37888
	ds_read_b128 v[212:215], v154 offset:38912
	ds_read_b128 v[216:219], v154 offset:39936
	global_load_lds_dwordx4 v134, s[56:57]
	s_mov_b32 m0, s33
	s_nop 0
	global_load_lds_dwordx4 v130, s[56:57]
	s_waitcnt vmcnt(8) lgkmcnt(0)
	s_setprio 1
	s_barrier
	v_mfma_f32_16x16x32_bf16 v[124:127], v[156:159], v[188:191], v[124:127]
	v_mfma_f32_16x16x32_bf16 v[120:123], v[164:167], v[188:191], v[120:123]
	v_mfma_f32_16x16x32_bf16 v[112:115], v[156:159], v[196:199], v[112:115]
	v_mfma_f32_16x16x32_bf16 v[104:107], v[164:167], v[196:199], v[104:107]
	v_mfma_f32_16x16x32_bf16 v[96:99], v[156:159], v[204:207], v[96:99]
	v_mfma_f32_16x16x32_bf16 v[88:91], v[164:167], v[204:207], v[88:91]
	v_mfma_f32_16x16x32_bf16 v[80:83], v[156:159], v[212:215], v[80:83]
	v_mfma_f32_16x16x32_bf16 v[72:75], v[164:167], v[212:215], v[72:75]
	v_mfma_f32_16x16x32_bf16 v[124:127], v[160:163], v[192:195], v[124:127]
	v_mfma_f32_16x16x32_bf16 v[120:123], v[168:171], v[192:195], v[120:123]
	v_mfma_f32_16x16x32_bf16 v[112:115], v[160:163], v[200:203], v[112:115]
	v_mfma_f32_16x16x32_bf16 v[104:107], v[168:171], v[200:203], v[104:107]
	v_mfma_f32_16x16x32_bf16 v[96:99], v[160:163], v[208:211], v[96:99]
	v_mfma_f32_16x16x32_bf16 v[88:91], v[168:171], v[208:211], v[88:91]
	v_mfma_f32_16x16x32_bf16 v[80:83], v[160:163], v[216:219], v[80:83]
	v_mfma_f32_16x16x32_bf16 v[72:75], v[168:171], v[216:219], v[72:75]
	v_mfma_f32_16x16x32_bf16 v[116:119], v[172:175], v[188:191], v[116:119]
	v_mfma_f32_16x16x32_bf16 v[108:111], v[180:183], v[188:191], v[108:111]
	v_mfma_f32_16x16x32_bf16 v[100:103], v[172:175], v[196:199], v[100:103]
	v_mfma_f32_16x16x32_bf16 v[92:95], v[180:183], v[196:199], v[92:95]
	v_mfma_f32_16x16x32_bf16 v[84:87], v[172:175], v[204:207], v[84:87]
	v_mfma_f32_16x16x32_bf16 v[76:79], v[180:183], v[204:207], v[76:79]
	v_mfma_f32_16x16x32_bf16 v[68:71], v[172:175], v[212:215], v[68:71]
	v_mfma_f32_16x16x32_bf16 v[64:67], v[180:183], v[212:215], v[64:67]
	v_mfma_f32_16x16x32_bf16 v[116:119], v[176:179], v[192:195], v[116:119]
	v_mfma_f32_16x16x32_bf16 v[108:111], v[184:187], v[192:195], v[108:111]
	v_mfma_f32_16x16x32_bf16 v[100:103], v[176:179], v[200:203], v[100:103]
	v_mfma_f32_16x16x32_bf16 v[92:95], v[184:187], v[200:203], v[92:95]
	v_mfma_f32_16x16x32_bf16 v[84:87], v[176:179], v[208:211], v[84:87]
	v_mfma_f32_16x16x32_bf16 v[76:79], v[184:187], v[208:211], v[76:79]
	v_mfma_f32_16x16x32_bf16 v[68:71], v[176:179], v[216:219], v[68:71]
	v_mfma_f32_16x16x32_bf16 v[64:67], v[184:187], v[216:219], v[64:67]
	s_barrier
	s_setprio 0
	s_add_i32 s56, s65, s24
	s_add_i32 m0, s56, -128
	ds_read_b128 v[188:191], v154 offset:49152
	ds_read_b128 v[192:195], v154 offset:50176
	ds_read_b128 v[196:199], v154 offset:51200
	ds_read_b128 v[200:203], v154 offset:52224
	ds_read_b128 v[204:207], v154 offset:53248
	ds_read_b128 v[208:211], v154 offset:54272
	ds_read_b128 v[212:215], v154 offset:55296
	ds_read_b128 v[216:219], v154 offset:56320
	global_load_lds_dwordx4 v132, s[40:41] offset:128
	s_add_i32 m0, s56, 8064
	s_add_u32 s40, s40, 0x100080
	s_addc_u32 s41, s41, 0
	s_add_i32 s56, s66, s24
	global_load_lds_dwordx4 v128, s[98:99] offset:128
	s_mov_b32 m0, s56
	s_nop 0
	global_load_lds_dwordx4 v132, s[40:41]
	s_add_i32 m0, s56, 0x2000
	s_nop 0
	global_load_lds_dwordx4 v128, s[40:41]
	s_add_i32 m0, s54, -128
	s_nop 0
	global_load_lds_dwordx4 v134, s[100:101] offset:128
	s_add_i32 m0, s55, -128
	s_nop 0
	global_load_lds_dwordx4 v130, s[100:101] offset:128
	s_waitcnt vmcnt(8) lgkmcnt(0)
	s_setprio 1
	s_barrier
	v_mfma_f32_16x16x32_bf16 v[60:63], v[156:159], v[188:191], v[60:63]
	v_mfma_f32_16x16x32_bf16 v[56:59], v[164:167], v[188:191], v[56:59]
	v_mfma_f32_16x16x32_bf16 v[52:55], v[156:159], v[196:199], v[52:55]
	v_mfma_f32_16x16x32_bf16 v[44:47], v[164:167], v[196:199], v[44:47]
	v_mfma_f32_16x16x32_bf16 v[36:39], v[156:159], v[204:207], v[36:39]
	v_mfma_f32_16x16x32_bf16 v[28:31], v[164:167], v[204:207], v[28:31]
	v_mfma_f32_16x16x32_bf16 v[20:23], v[156:159], v[212:215], v[20:23]
	v_mfma_f32_16x16x32_bf16 v[12:15], v[164:167], v[212:215], v[12:15]
	v_mfma_f32_16x16x32_bf16 v[60:63], v[160:163], v[192:195], v[60:63]
	v_mfma_f32_16x16x32_bf16 v[56:59], v[168:171], v[192:195], v[56:59]
	v_mfma_f32_16x16x32_bf16 v[52:55], v[160:163], v[200:203], v[52:55]
	v_mfma_f32_16x16x32_bf16 v[44:47], v[168:171], v[200:203], v[44:47]
	v_mfma_f32_16x16x32_bf16 v[36:39], v[160:163], v[208:211], v[36:39]
	v_mfma_f32_16x16x32_bf16 v[28:31], v[168:171], v[208:211], v[28:31]
	v_mfma_f32_16x16x32_bf16 v[20:23], v[160:163], v[216:219], v[20:23]
	v_mfma_f32_16x16x32_bf16 v[12:15], v[168:171], v[216:219], v[12:15]
	v_mfma_f32_16x16x32_bf16 v[48:51], v[172:175], v[188:191], v[48:51]
	v_mfma_f32_16x16x32_bf16 v[40:43], v[180:183], v[188:191], v[40:43]
	v_mfma_f32_16x16x32_bf16 v[32:35], v[172:175], v[196:199], v[32:35]
	v_mfma_f32_16x16x32_bf16 v[24:27], v[180:183], v[196:199], v[24:27]
	v_mfma_f32_16x16x32_bf16 v[16:19], v[172:175], v[204:207], v[16:19]
	v_mfma_f32_16x16x32_bf16 v[8:11], v[180:183], v[204:207], v[8:11]
	v_mfma_f32_16x16x32_bf16 v[4:7], v[172:175], v[212:215], v[4:7]
	v_mfma_f32_16x16x32_bf16 v[0:3], v[180:183], v[212:215], v[0:3]
	v_mfma_f32_16x16x32_bf16 v[48:51], v[176:179], v[192:195], v[48:51]
	v_mfma_f32_16x16x32_bf16 v[40:43], v[184:187], v[192:195], v[40:43]
	v_mfma_f32_16x16x32_bf16 v[32:35], v[176:179], v[200:203], v[32:35]
	v_mfma_f32_16x16x32_bf16 v[24:27], v[184:187], v[200:203], v[24:27]
	v_mfma_f32_16x16x32_bf16 v[16:19], v[176:179], v[208:211], v[16:19]
	v_mfma_f32_16x16x32_bf16 v[8:11], v[184:187], v[208:211], v[8:11]
	v_mfma_f32_16x16x32_bf16 v[4:7], v[176:179], v[216:219], v[4:7]
	v_mfma_f32_16x16x32_bf16 v[0:3], v[184:187], v[216:219], v[0:3]
	s_barrier
	s_setprio 0
	s_add_i32 s64, s64, 2
	s_add_u32 s38, s38, 0x100
	s_addc_u32 s39, s39, 0
	s_add_u32 s62, s62, 0x100
	s_addc_u32 s63, s63, 0
	s_cmp_gt_u32 s64, 61
	s_cbranch_scc0 .LBB0_394
	s_and_b64 vcc, exec, s[12:13]
	s_cbranch_vccz .LBB0_397
	s_barrier

.LBB0_489:
	s_andn2_b64 vcc, exec, s[38:39]
	s_cbranch_vccnz .LBB0_491
	s_lshl_b32 s4, s77, 15
	s_add_i32 s4, s4, 0
	s_add_i32 s4, s4, 0x8000
	v_add_u32_e32 v229, s4, v213
	v_add_u32_e32 v230, v229, v218
	ds_read_b64_tr_b16 v[176:177], v230 offset:0
	ds_read_b64_tr_b16 v[178:179], v230 offset:0x1000
	v_add_u32_e32 v231, v229, v219
	ds_read_b64_tr_b16 v[180:181], v231 offset:0
	ds_read_b64_tr_b16 v[182:183], v231 offset:0x1000
	v_add_u32_e32 v232, v229, v220
	ds_read_b64_tr_b16 v[184:185], v232 offset:0
	ds_read_b64_tr_b16 v[186:187], v232 offset:0x1000
	v_add_u32_e32 v233, v229, v221
	ds_read_b64_tr_b16 v[188:189], v233 offset:0
	ds_read_b64_tr_b16 v[190:191], v233 offset:0x1000
	s_waitcnt lgkmcnt(6)
	v_mfma_f32_16x16x32_bf16 v[156:159], v[176:179], v[160:163], v[156:159]
	v_add_u32_e32 v234, v229, v222
	v_add_u32_e32 v235, v229, v223
	v_add_u32_e32 v236, v229, v224
	v_mfma_f32_16x16x32_bf16 v[92:95], v[176:179], v[168:171], v[92:95]
	ds_read_b64_tr_b16 v[176:177], v234 offset:0
	ds_read_b64_tr_b16 v[178:179], v234 offset:0x1000
	v_add_u32_e32 v229, v229, v225
	s_waitcnt lgkmcnt(6)
	v_mfma_f32_16x16x32_bf16 v[152:155], v[180:183], v[160:163], v[152:155]
	v_mfma_f32_16x16x32_bf16 v[88:91], v[180:183], v[168:171], v[88:91]
	ds_read_b64_tr_b16 v[180:181], v235 offset:0
	ds_read_b64_tr_b16 v[182:183], v235 offset:0x1000
	s_waitcnt lgkmcnt(6)
	v_mfma_f32_16x16x32_bf16 v[148:151], v[184:187], v[160:163], v[148:151]
	v_mfma_f32_16x16x32_bf16 v[84:87], v[184:187], v[168:171], v[84:87]
	ds_read_b64_tr_b16 v[184:185], v236 offset:0
	ds_read_b64_tr_b16 v[186:187], v236 offset:0x1000
	s_waitcnt lgkmcnt(6)
	v_mfma_f32_16x16x32_bf16 v[144:147], v[188:191], v[160:163], v[144:147]
	v_mfma_f32_16x16x32_bf16 v[80:83], v[188:191], v[168:171], v[80:83]
	ds_read_b64_tr_b16 v[188:189], v229 offset:0
	ds_read_b64_tr_b16 v[190:191], v229 offset:0x1000
	s_waitcnt lgkmcnt(6)
	v_mfma_f32_16x16x32_bf16 v[140:143], v[176:179], v[160:163], v[140:143]
	v_mfma_f32_16x16x32_bf16 v[76:79], v[176:179], v[168:171], v[76:79]
	ds_read_b64_tr_b16 v[176:177], v230 offset:0x4000
	ds_read_b64_tr_b16 v[178:179], v230 offset:0x5000
	s_waitcnt lgkmcnt(6)
	v_mfma_f32_16x16x32_bf16 v[136:139], v[180:183], v[160:163], v[136:139]
	v_mfma_f32_16x16x32_bf16 v[72:75], v[180:183], v[168:171], v[72:75]
	ds_read_b64_tr_b16 v[180:181], v231 offset:0x4000
	ds_read_b64_tr_b16 v[182:183], v231 offset:0x5000
	s_waitcnt lgkmcnt(6)
	v_mfma_f32_16x16x32_bf16 v[132:135], v[184:187], v[160:163], v[132:135]
	v_mfma_f32_16x16x32_bf16 v[40:43], v[184:187], v[168:171], v[40:43]
	ds_read_b64_tr_b16 v[184:185], v232 offset:0x4000
	ds_read_b64_tr_b16 v[186:187], v232 offset:0x5000
	s_waitcnt lgkmcnt(6)
	v_mfma_f32_16x16x32_bf16 v[128:131], v[188:191], v[160:163], v[128:131]
	v_mfma_f32_16x16x32_bf16 v[32:35], v[188:191], v[168:171], v[32:35]
	ds_read_b64_tr_b16 v[188:189], v233 offset:0x4000
	ds_read_b64_tr_b16 v[190:191], v233 offset:0x5000
	s_waitcnt lgkmcnt(6)
	v_mfma_f32_16x16x32_bf16 v[124:127], v[176:179], v[160:163], v[124:127]
	v_mfma_f32_16x16x32_bf16 v[28:31], v[176:179], v[168:171], v[28:31]
	ds_read_b64_tr_b16 v[176:177], v234 offset:0x4000
	ds_read_b64_tr_b16 v[178:179], v234 offset:0x5000
	s_waitcnt lgkmcnt(6)
	v_mfma_f32_16x16x32_bf16 v[120:123], v[180:183], v[160:163], v[120:123]
	v_mfma_f32_16x16x32_bf16 v[24:27], v[180:183], v[168:171], v[24:27]
	ds_read_b64_tr_b16 v[180:181], v235 offset:0x4000
	ds_read_b64_tr_b16 v[182:183], v235 offset:0x5000
	s_waitcnt lgkmcnt(6)
	v_mfma_f32_16x16x32_bf16 v[116:119], v[184:187], v[160:163], v[116:119]
	v_mfma_f32_16x16x32_bf16 v[20:23], v[184:187], v[168:171], v[20:23]
	ds_read_b64_tr_b16 v[184:185], v236 offset:0x4000
	ds_read_b64_tr_b16 v[186:187], v236 offset:0x5000
	s_waitcnt lgkmcnt(6)
	v_mfma_f32_16x16x32_bf16 v[112:115], v[188:191], v[160:163], v[112:115]
	v_mfma_f32_16x16x32_bf16 v[16:19], v[188:191], v[168:171], v[16:19]
	ds_read_b64_tr_b16 v[188:189], v229 offset:0x4000
	ds_read_b64_tr_b16 v[190:191], v229 offset:0x5000
	s_waitcnt lgkmcnt(6)
	v_mfma_f32_16x16x32_bf16 v[108:111], v[176:179], v[160:163], v[108:111]
	v_mfma_f32_16x16x32_bf16 v[8:11], v[176:179], v[168:171], v[8:11]
	ds_read_b64_tr_b16 v[176:177], v230 offset:0x2000
	ds_read_b64_tr_b16 v[178:179], v230 offset:0x3000
	s_waitcnt lgkmcnt(6)
	v_mfma_f32_16x16x32_bf16 v[104:107], v[180:183], v[160:163], v[104:107]
	v_mfma_f32_16x16x32_bf16 v[0:3], v[180:183], v[168:171], v[0:3]
	ds_read_b64_tr_b16 v[180:181], v231 offset:0x2000
	ds_read_b64_tr_b16 v[182:183], v231 offset:0x3000
	s_waitcnt lgkmcnt(6)
	v_mfma_f32_16x16x32_bf16 v[100:103], v[184:187], v[160:163], v[100:103]
	v_mfma_f32_16x16x32_bf16 v[12:15], v[184:187], v[168:171], v[12:15]
	ds_read_b64_tr_b16 v[184:185], v232 offset:0x2000
	ds_read_b64_tr_b16 v[186:187], v232 offset:0x3000
	s_waitcnt lgkmcnt(6)
	v_mfma_f32_16x16x32_bf16 v[96:99], v[188:191], v[160:163], v[96:99]
	v_mfma_f32_16x16x32_bf16 v[4:7], v[188:191], v[168:171], v[4:7]
	ds_read_b64_tr_b16 v[188:189], v233 offset:0x2000
	ds_read_b64_tr_b16 v[190:191], v233 offset:0x3000
	s_waitcnt lgkmcnt(6)
	v_mfma_f32_16x16x32_bf16 v[156:159], v[176:179], v[164:167], v[156:159]
	v_mfma_f32_16x16x32_bf16 v[92:95], v[176:179], v[172:175], v[92:95]
	ds_read_b64_tr_b16 v[176:177], v234 offset:0x2000
	ds_read_b64_tr_b16 v[178:179], v234 offset:0x3000
	s_waitcnt lgkmcnt(6)
	v_mfma_f32_16x16x32_bf16 v[152:155], v[180:183], v[164:167], v[152:155]
	v_mfma_f32_16x16x32_bf16 v[88:91], v[180:183], v[172:175], v[88:91]
	ds_read_b64_tr_b16 v[180:181], v235 offset:0x2000
	ds_read_b64_tr_b16 v[182:183], v235 offset:0x3000
	s_waitcnt lgkmcnt(6)
	v_mfma_f32_16x16x32_bf16 v[148:151], v[184:187], v[164:167], v[148:151]
	v_mfma_f32_16x16x32_bf16 v[84:87], v[184:187], v[172:175], v[84:87]
	ds_read_b64_tr_b16 v[184:185], v236 offset:0x2000
	ds_read_b64_tr_b16 v[186:187], v236 offset:0x3000
	s_waitcnt lgkmcnt(6)
	v_mfma_f32_16x16x32_bf16 v[144:147], v[188:191], v[164:167], v[144:147]
	v_mfma_f32_16x16x32_bf16 v[80:83], v[188:191], v[172:175], v[80:83]
	ds_read_b64_tr_b16 v[188:189], v229 offset:0x2000
	ds_read_b64_tr_b16 v[190:191], v229 offset:0x3000
	s_waitcnt lgkmcnt(6)
	v_mfma_f32_16x16x32_bf16 v[140:143], v[176:179], v[164:167], v[140:143]
	v_mfma_f32_16x16x32_bf16 v[76:79], v[176:179], v[172:175], v[76:79]
	ds_read_b64_tr_b16 v[176:177], v230 offset:0x6000
	ds_read_b64_tr_b16 v[178:179], v230 offset:0x7000
	s_waitcnt lgkmcnt(6)
	v_mfma_f32_16x16x32_bf16 v[136:139], v[180:183], v[164:167], v[136:139]
	v_mfma_f32_16x16x32_bf16 v[72:75], v[180:183], v[172:175], v[72:75]
	ds_read_b64_tr_b16 v[180:181], v231 offset:0x6000
	ds_read_b64_tr_b16 v[182:183], v231 offset:0x7000
	s_waitcnt lgkmcnt(6)
	v_mfma_f32_16x16x32_bf16 v[132:135], v[184:187], v[164:167], v[132:135]
	v_mfma_f32_16x16x32_bf16 v[40:43], v[184:187], v[172:175], v[40:43]
	ds_read_b64_tr_b16 v[184:185], v232 offset:0x6000
	ds_read_b64_tr_b16 v[186:187], v232 offset:0x7000
	s_waitcnt lgkmcnt(6)
	v_mfma_f32_16x16x32_bf16 v[128:131], v[188:191], v[164:167], v[128:131]
	v_mfma_f32_16x16x32_bf16 v[32:35], v[188:191], v[172:175], v[32:35]
	ds_read_b64_tr_b16 v[188:189], v233 offset:0x6000
	ds_read_b64_tr_b16 v[190:191], v233 offset:0x7000
	s_waitcnt lgkmcnt(6)
	v_mfma_f32_16x16x32_bf16 v[124:127], v[176:179], v[164:167], v[124:127]
	v_mfma_f32_16x16x32_bf16 v[28:31], v[176:179], v[172:175], v[28:31]
	ds_read_b64_tr_b16 v[176:177], v234 offset:0x6000
	ds_read_b64_tr_b16 v[178:179], v234 offset:0x7000
	s_waitcnt lgkmcnt(6)
	v_mfma_f32_16x16x32_bf16 v[120:123], v[180:183], v[164:167], v[120:123]
	v_mfma_f32_16x16x32_bf16 v[24:27], v[180:183], v[172:175], v[24:27]
	ds_read_b64_tr_b16 v[180:181], v235 offset:0x6000
	ds_read_b64_tr_b16 v[182:183], v235 offset:0x7000
	s_waitcnt lgkmcnt(6)
	v_mfma_f32_16x16x32_bf16 v[116:119], v[184:187], v[164:167], v[116:119]
	v_mfma_f32_16x16x32_bf16 v[20:23], v[184:187], v[172:175], v[20:23]
	ds_read_b64_tr_b16 v[184:185], v236 offset:0x6000
	ds_read_b64_tr_b16 v[186:187], v236 offset:0x7000
	s_waitcnt lgkmcnt(6)
	v_mfma_f32_16x16x32_bf16 v[112:115], v[188:191], v[164:167], v[112:115]
	v_mfma_f32_16x16x32_bf16 v[16:19], v[188:191], v[172:175], v[16:19]
	ds_read_b64_tr_b16 v[188:189], v229 offset:0x6000
	ds_read_b64_tr_b16 v[190:191], v229 offset:0x7000
	s_waitcnt lgkmcnt(6)
	v_mfma_f32_16x16x32_bf16 v[108:111], v[176:179], v[164:167], v[108:111]
	v_mfma_f32_16x16x32_bf16 v[8:11], v[176:179], v[172:175], v[8:11]
	s_waitcnt lgkmcnt(4)
	v_mfma_f32_16x16x32_bf16 v[104:107], v[180:183], v[164:167], v[104:107]
	v_mfma_f32_16x16x32_bf16 v[0:3], v[180:183], v[172:175], v[0:3]
	s_waitcnt lgkmcnt(2)
	v_mfma_f32_16x16x32_bf16 v[100:103], v[184:187], v[164:167], v[100:103]
	v_mfma_f32_16x16x32_bf16 v[12:15], v[184:187], v[172:175], v[12:15]
	s_waitcnt lgkmcnt(0)
	v_mfma_f32_16x16x32_bf16 v[96:99], v[188:191], v[164:167], v[96:99]
	v_mfma_f32_16x16x32_bf16 v[4:7], v[188:191], v[172:175], v[4:7]

.LBB0_622:
	ds_read_b128 v[152:155], v149
	ds_read_b128 v[156:159], v149 offset:1024
	ds_read_b128 v[160:163], v149 offset:2048
	ds_read_b128 v[164:167], v149 offset:3072
	ds_read_b128 v[168:171], v150
	ds_read_b128 v[172:175], v150 offset:1024
	ds_read_b128 v[176:179], v150 offset:2048
	ds_read_b128 v[180:183], v150 offset:3072
	s_add_u32 s42, s40, 0xfff00080
	s_addc_u32 s43, s41, -1
	s_cmp_eq_u32 s61, 60
	s_cselect_b32 s45, s25, s43
	s_cselect_b32 s44, s57, s42
	s_cselect_b32 s43, s23, s60
	s_cselect_b32 s42, s58, s59
	s_add_i32 m0, s31, 0xc000
	ds_read_b128 v[184:187], v151
	ds_read_b128 v[188:191], v151 offset:1024
	ds_read_b128 v[192:195], v151 offset:2048
	ds_read_b128 v[196:199], v151 offset:3072
	ds_read_b128 v[200:203], v151 offset:4096
	ds_read_b128 v[204:207], v151 offset:5120
	ds_read_b128 v[208:211], v151 offset:6144
	ds_read_b128 v[212:215], v151 offset:7168
	global_load_lds_dwordx4 v136, s[40:41]
	s_add_i32 m0, s31, 0xe000
	s_nop 0
	global_load_lds_dwordx4 v138, s[40:41]
	s_waitcnt vmcnt(8) lgkmcnt(0)
	s_setprio 1
	s_barrier
	v_mfma_f32_16x16x32_bf16 v[124:127], v[152:155], v[184:187], v[124:127]
	v_mfma_f32_16x16x32_bf16 v[120:123], v[160:163], v[184:187], v[120:123]
	v_mfma_f32_16x16x32_bf16 v[116:119], v[152:155], v[192:195], v[116:119]
	v_mfma_f32_16x16x32_bf16 v[108:111], v[160:163], v[192:195], v[108:111]
	v_mfma_f32_16x16x32_bf16 v[100:103], v[152:155], v[200:203], v[100:103]
	v_mfma_f32_16x16x32_bf16 v[92:95], v[160:163], v[200:203], v[92:95]
	v_mfma_f32_16x16x32_bf16 v[84:87], v[152:155], v[208:211], v[84:87]
	v_mfma_f32_16x16x32_bf16 v[76:79], v[160:163], v[208:211], v[76:79]
	v_mfma_f32_16x16x32_bf16 v[124:127], v[156:159], v[188:191], v[124:127]
	v_mfma_f32_16x16x32_bf16 v[120:123], v[164:167], v[188:191], v[120:123]
	v_mfma_f32_16x16x32_bf16 v[116:119], v[156:159], v[196:199], v[116:119]
	v_mfma_f32_16x16x32_bf16 v[108:111], v[164:167], v[196:199], v[108:111]
	v_mfma_f32_16x16x32_bf16 v[100:103], v[156:159], v[204:207], v[100:103]
	v_mfma_f32_16x16x32_bf16 v[92:95], v[164:167], v[204:207], v[92:95]
	v_mfma_f32_16x16x32_bf16 v[84:87], v[156:159], v[212:215], v[84:87]
	v_mfma_f32_16x16x32_bf16 v[76:79], v[164:167], v[212:215], v[76:79]
	v_mfma_f32_16x16x32_bf16 v[112:115], v[168:171], v[184:187], v[112:115]
	v_mfma_f32_16x16x32_bf16 v[104:107], v[176:179], v[184:187], v[104:107]
	v_mfma_f32_16x16x32_bf16 v[96:99], v[168:171], v[192:195], v[96:99]
	v_mfma_f32_16x16x32_bf16 v[88:91], v[176:179], v[192:195], v[88:91]
	v_mfma_f32_16x16x32_bf16 v[80:83], v[168:171], v[200:203], v[80:83]
	v_mfma_f32_16x16x32_bf16 v[72:75], v[176:179], v[200:203], v[72:75]
	v_mfma_f32_16x16x32_bf16 v[68:71], v[168:171], v[208:211], v[68:71]
	v_mfma_f32_16x16x32_bf16 v[64:67], v[176:179], v[208:211], v[64:67]
	v_mfma_f32_16x16x32_bf16 v[112:115], v[172:175], v[188:191], v[112:115]
	v_mfma_f32_16x16x32_bf16 v[104:107], v[180:183], v[188:191], v[104:107]
	v_mfma_f32_16x16x32_bf16 v[96:99], v[172:175], v[196:199], v[96:99]
	v_mfma_f32_16x16x32_bf16 v[88:91], v[180:183], v[196:199], v[88:91]
	v_mfma_f32_16x16x32_bf16 v[80:83], v[172:175], v[204:207], v[80:83]
	v_mfma_f32_16x16x32_bf16 v[72:75], v[180:183], v[204:207], v[72:75]
	v_mfma_f32_16x16x32_bf16 v[68:71], v[172:175], v[212:215], v[68:71]
	v_mfma_f32_16x16x32_bf16 v[64:67], v[180:183], v[212:215], v[64:67]
	s_barrier
	s_setprio 0
	s_add_i32 s62, s50, s29
	s_mov_b32 m0, s62
	ds_read_b128 v[184:187], v151 offset:16384
	ds_read_b128 v[188:191], v151 offset:17408
	ds_read_b128 v[192:195], v151 offset:18432
	ds_read_b128 v[196:199], v151 offset:19456
	ds_read_b128 v[200:203], v151 offset:20480
	ds_read_b128 v[204:207], v151 offset:21504
	ds_read_b128 v[208:211], v151 offset:22528
	ds_read_b128 v[212:215], v151 offset:23552
	global_load_lds_dwordx4 v132, s[42:43]
	s_add_i32 m0, s62, 0x2000
	s_add_u32 s62, s42, 0x100000
	s_mov_b64 s[98:99], s[42:43]
	s_addc_u32 s63, s43, 0
	s_add_i32 s64, s51, s29
	global_load_lds_dwordx4 v128, s[98:99]
	s_mov_b32 m0, s64
	s_mov_b64 s[100:101], s[44:45]
	global_load_lds_dwordx4 v132, s[62:63]
	s_add_i32 m0, s64, 0x2000
	s_nop 0
	global_load_lds_dwordx4 v128, s[62:63]
	s_mov_b64 s[100:101], s[44:45]
	s_mov_b32 m0, s31
	s_nop 0
	global_load_lds_dwordx4 v134, s[100:101]
	s_mov_b32 m0, s33
	s_nop 0
	global_load_lds_dwordx4 v130, s[100:101]
	s_waitcnt vmcnt(8) lgkmcnt(0)
	s_setprio 1
	s_barrier
	v_mfma_f32_16x16x32_bf16 v[60:63], v[152:155], v[184:187], v[60:63]
	v_mfma_f32_16x16x32_bf16 v[56:59], v[160:163], v[184:187], v[56:59]
	v_mfma_f32_16x16x32_bf16 v[52:55], v[152:155], v[192:195], v[52:55]
	v_mfma_f32_16x16x32_bf16 v[44:47], v[160:163], v[192:195], v[44:47]
	v_mfma_f32_16x16x32_bf16 v[36:39], v[152:155], v[200:203], v[36:39]
	v_mfma_f32_16x16x32_bf16 v[28:31], v[160:163], v[200:203], v[28:31]
	v_mfma_f32_16x16x32_bf16 v[20:23], v[152:155], v[208:211], v[20:23]
	v_mfma_f32_16x16x32_bf16 v[12:15], v[160:163], v[208:211], v[12:15]
	v_mfma_f32_16x16x32_bf16 v[60:63], v[156:159], v[188:191], v[60:63]
	v_mfma_f32_16x16x32_bf16 v[56:59], v[164:167], v[188:191], v[56:59]
	v_mfma_f32_16x16x32_bf16 v[52:55], v[156:159], v[196:199], v[52:55]
	v_mfma_f32_16x16x32_bf16 v[44:47], v[164:167], v[196:199], v[44:47]
	v_mfma_f32_16x16x32_bf16 v[36:39], v[156:159], v[204:207], v[36:39]
	v_mfma_f32_16x16x32_bf16 v[28:31], v[164:167], v[204:207], v[28:31]
	v_mfma_f32_16x16x32_bf16 v[20:23], v[156:159], v[212:215], v[20:23]
	v_mfma_f32_16x16x32_bf16 v[12:15], v[164:167], v[212:215], v[12:15]
	v_mfma_f32_16x16x32_bf16 v[48:51], v[168:171], v[184:187], v[48:51]
	v_mfma_f32_16x16x32_bf16 v[40:43], v[176:179], v[184:187], v[40:43]
	v_mfma_f32_16x16x32_bf16 v[32:35], v[168:171], v[192:195], v[32:35]
	v_mfma_f32_16x16x32_bf16 v[24:27], v[176:179], v[192:195], v[24:27]
	v_mfma_f32_16x16x32_bf16 v[16:19], v[168:171], v[200:203], v[16:19]
	v_mfma_f32_16x16x32_bf16 v[8:11], v[176:179], v[200:203], v[8:11]
	v_mfma_f32_16x16x32_bf16 v[4:7], v[168:171], v[208:211], v[4:7]
	v_mfma_f32_16x16x32_bf16 v[0:3], v[176:179], v[208:211], v[0:3]
	v_mfma_f32_16x16x32_bf16 v[48:51], v[172:175], v[188:191], v[48:51]
	v_mfma_f32_16x16x32_bf16 v[40:43], v[180:183], v[188:191], v[40:43]
	v_mfma_f32_16x16x32_bf16 v[32:35], v[172:175], v[196:199], v[32:35]
	v_mfma_f32_16x16x32_bf16 v[24:27], v[180:183], v[196:199], v[24:27]
	v_mfma_f32_16x16x32_bf16 v[16:19], v[172:175], v[204:207], v[16:19]
	v_mfma_f32_16x16x32_bf16 v[8:11], v[180:183], v[204:207], v[8:11]
	v_mfma_f32_16x16x32_bf16 v[4:7], v[172:175], v[212:215], v[4:7]
	v_mfma_f32_16x16x32_bf16 v[0:3], v[180:183], v[212:215], v[0:3]
	s_barrier
	s_setprio 0
	s_add_i32 s62, 0, 0x18000
	s_add_i32 s63, 0, 0x1c000
	ds_read_b128 v[152:155], v149 offset:32768
	ds_read_b128 v[156:159], v149 offset:33792
	ds_read_b128 v[160:163], v149 offset:34816
	ds_read_b128 v[164:167], v149 offset:35840
	ds_read_b128 v[168:171], v150 offset:32768
	ds_read_b128 v[172:175], v150 offset:33792
	ds_read_b128 v[176:179], v150 offset:34816
	ds_read_b128 v[180:183], v150 offset:35840
	s_add_u32 s44, s44, 0x100000
	s_addc_u32 s45, s45, 0
	s_mov_b32 m0, s35
	ds_read_b128 v[184:187], v151 offset:32768
	ds_read_b128 v[188:191], v151 offset:33792
	ds_read_b128 v[192:195], v151 offset:34816
	ds_read_b128 v[196:199], v151 offset:35840
	ds_read_b128 v[200:203], v151 offset:36864
	ds_read_b128 v[204:207], v151 offset:37888
	ds_read_b128 v[208:211], v151 offset:38912
	ds_read_b128 v[212:215], v151 offset:39936
	global_load_lds_dwordx4 v134, s[44:45]
	s_mov_b32 m0, s39
	s_nop 0
	global_load_lds_dwordx4 v130, s[44:45]
	s_waitcnt vmcnt(8) lgkmcnt(0)
	s_setprio 1
	s_barrier
	v_mfma_f32_16x16x32_bf16 v[124:127], v[152:155], v[184:187], v[124:127]
	v_mfma_f32_16x16x32_bf16 v[120:123], v[160:163], v[184:187], v[120:123]
	v_mfma_f32_16x16x32_bf16 v[116:119], v[152:155], v[192:195], v[116:119]
	v_mfma_f32_16x16x32_bf16 v[108:111], v[160:163], v[192:195], v[108:111]
	v_mfma_f32_16x16x32_bf16 v[100:103], v[152:155], v[200:203], v[100:103]
	v_mfma_f32_16x16x32_bf16 v[92:95], v[160:163], v[200:203], v[92:95]
	v_mfma_f32_16x16x32_bf16 v[84:87], v[152:155], v[208:211], v[84:87]
	v_mfma_f32_16x16x32_bf16 v[76:79], v[160:163], v[208:211], v[76:79]
	v_mfma_f32_16x16x32_bf16 v[124:127], v[156:159], v[188:191], v[124:127]
	v_mfma_f32_16x16x32_bf16 v[120:123], v[164:167], v[188:191], v[120:123]
	v_mfma_f32_16x16x32_bf16 v[116:119], v[156:159], v[196:199], v[116:119]
	v_mfma_f32_16x16x32_bf16 v[108:111], v[164:167], v[196:199], v[108:111]
	v_mfma_f32_16x16x32_bf16 v[100:103], v[156:159], v[204:207], v[100:103]
	v_mfma_f32_16x16x32_bf16 v[92:95], v[164:167], v[204:207], v[92:95]
	v_mfma_f32_16x16x32_bf16 v[84:87], v[156:159], v[212:215], v[84:87]
	v_mfma_f32_16x16x32_bf16 v[76:79], v[164:167], v[212:215], v[76:79]
	v_mfma_f32_16x16x32_bf16 v[112:115], v[168:171], v[184:187], v[112:115]
	v_mfma_f32_16x16x32_bf16 v[104:107], v[176:179], v[184:187], v[104:107]
	v_mfma_f32_16x16x32_bf16 v[96:99], v[168:171], v[192:195], v[96:99]
	v_mfma_f32_16x16x32_bf16 v[88:91], v[176:179], v[192:195], v[88:91]
	v_mfma_f32_16x16x32_bf16 v[80:83], v[168:171], v[200:203], v[80:83]
	v_mfma_f32_16x16x32_bf16 v[72:75], v[176:179], v[200:203], v[72:75]
	v_mfma_f32_16x16x32_bf16 v[68:71], v[168:171], v[208:211], v[68:71]
	v_mfma_f32_16x16x32_bf16 v[64:67], v[176:179], v[208:211], v[64:67]
	v_mfma_f32_16x16x32_bf16 v[112:115], v[172:175], v[188:191], v[112:115]
	v_mfma_f32_16x16x32_bf16 v[104:107], v[180:183], v[188:191], v[104:107]
	v_mfma_f32_16x16x32_bf16 v[96:99], v[172:175], v[196:199], v[96:99]
	v_mfma_f32_16x16x32_bf16 v[88:91], v[180:183], v[196:199], v[88:91]
	v_mfma_f32_16x16x32_bf16 v[80:83], v[172:175], v[204:207], v[80:83]
	v_mfma_f32_16x16x32_bf16 v[72:75], v[180:183], v[204:207], v[72:75]
	v_mfma_f32_16x16x32_bf16 v[68:71], v[172:175], v[212:215], v[68:71]
	v_mfma_f32_16x16x32_bf16 v[64:67], v[180:183], v[212:215], v[64:67]
	s_barrier
	s_setprio 0
	s_add_i32 s44, s62, s29
	s_add_i32 m0, s44, -128
	ds_read_b128 v[184:187], v151 offset:49152
	ds_read_b128 v[188:191], v151 offset:50176
	ds_read_b128 v[192:195], v151 offset:51200
	ds_read_b128 v[196:199], v151 offset:52224
	ds_read_b128 v[200:203], v151 offset:53248
	ds_read_b128 v[204:207], v151 offset:54272
	ds_read_b128 v[208:211], v151 offset:55296
	ds_read_b128 v[212:215], v151 offset:56320
	global_load_lds_dwordx4 v132, s[42:43] offset:128
	s_add_i32 m0, s44, 8064
	s_add_u32 s42, s42, 0x100080
	s_addc_u32 s43, s43, 0
	s_add_i32 s44, s63, s29
	global_load_lds_dwordx4 v128, s[98:99] offset:128
	s_mov_b32 m0, s44
	s_nop 0
	global_load_lds_dwordx4 v132, s[42:43]
	s_add_i32 m0, s44, 0x2000
	s_nop 0
	global_load_lds_dwordx4 v128, s[42:43]
	s_add_i32 m0, s48, -128
	s_nop 0
	global_load_lds_dwordx4 v134, s[100:101] offset:128
	s_add_i32 m0, s49, -128
	s_nop 0
	global_load_lds_dwordx4 v130, s[100:101] offset:128
	s_waitcnt vmcnt(8) lgkmcnt(0)
	s_setprio 1
	s_barrier
	v_mfma_f32_16x16x32_bf16 v[60:63], v[152:155], v[184:187], v[60:63]
	v_mfma_f32_16x16x32_bf16 v[56:59], v[160:163], v[184:187], v[56:59]
	v_mfma_f32_16x16x32_bf16 v[52:55], v[152:155], v[192:195], v[52:55]
	v_mfma_f32_16x16x32_bf16 v[44:47], v[160:163], v[192:195], v[44:47]
	v_mfma_f32_16x16x32_bf16 v[36:39], v[152:155], v[200:203], v[36:39]
	v_mfma_f32_16x16x32_bf16 v[28:31], v[160:163], v[200:203], v[28:31]
	v_mfma_f32_16x16x32_bf16 v[20:23], v[152:155], v[208:211], v[20:23]
	v_mfma_f32_16x16x32_bf16 v[12:15], v[160:163], v[208:211], v[12:15]
	v_mfma_f32_16x16x32_bf16 v[60:63], v[156:159], v[188:191], v[60:63]
	v_mfma_f32_16x16x32_bf16 v[56:59], v[164:167], v[188:191], v[56:59]
	v_mfma_f32_16x16x32_bf16 v[52:55], v[156:159], v[196:199], v[52:55]
	v_mfma_f32_16x16x32_bf16 v[44:47], v[164:167], v[196:199], v[44:47]
	v_mfma_f32_16x16x32_bf16 v[36:39], v[156:159], v[204:207], v[36:39]
	v_mfma_f32_16x16x32_bf16 v[28:31], v[164:167], v[204:207], v[28:31]
	v_mfma_f32_16x16x32_bf16 v[20:23], v[156:159], v[212:215], v[20:23]
	v_mfma_f32_16x16x32_bf16 v[12:15], v[164:167], v[212:215], v[12:15]
	v_mfma_f32_16x16x32_bf16 v[48:51], v[168:171], v[184:187], v[48:51]
	v_mfma_f32_16x16x32_bf16 v[40:43], v[176:179], v[184:187], v[40:43]
	v_mfma_f32_16x16x32_bf16 v[32:35], v[168:171], v[192:195], v[32:35]
	v_mfma_f32_16x16x32_bf16 v[24:27], v[176:179], v[192:195], v[24:27]
	v_mfma_f32_16x16x32_bf16 v[16:19], v[168:171], v[200:203], v[16:19]
	v_mfma_f32_16x16x32_bf16 v[8:11], v[176:179], v[200:203], v[8:11]
	v_mfma_f32_16x16x32_bf16 v[4:7], v[168:171], v[208:211], v[4:7]
	v_mfma_f32_16x16x32_bf16 v[0:3], v[176:179], v[208:211], v[0:3]
	v_mfma_f32_16x16x32_bf16 v[48:51], v[172:175], v[188:191], v[48:51]
	v_mfma_f32_16x16x32_bf16 v[40:43], v[180:183], v[188:191], v[40:43]
	v_mfma_f32_16x16x32_bf16 v[32:35], v[172:175], v[196:199], v[32:35]
	v_mfma_f32_16x16x32_bf16 v[24:27], v[180:183], v[196:199], v[24:27]
	v_mfma_f32_16x16x32_bf16 v[16:19], v[172:175], v[204:207], v[16:19]
	v_mfma_f32_16x16x32_bf16 v[8:11], v[180:183], v[204:207], v[8:11]
	v_mfma_f32_16x16x32_bf16 v[4:7], v[172:175], v[212:215], v[4:7]
	v_mfma_f32_16x16x32_bf16 v[0:3], v[180:183], v[212:215], v[0:3]
	s_barrier
	s_setprio 0
	s_add_i32 s61, s61, 2
	s_add_u32 s40, s40, 0x100
	s_addc_u32 s41, s41, 0
	s_add_u32 s59, s59, 0x100
	s_addc_u32 s60, s60, 0
	s_cmp_gt_u32 s61, 61
	s_cbranch_scc0 .LBB0_622
	s_and_b64 vcc, exec, s[10:11]
	s_cbranch_vccz .LBB0_625
	s_barrier

.LBB0_773:
	ds_read_b128 v[144:147], v155
	ds_read_b128 v[148:151], v155 offset:1024
	ds_read_b128 v[158:161], v155 offset:2048
	ds_read_b128 v[162:165], v155 offset:3072
	ds_read_b128 v[166:169], v156
	ds_read_b128 v[170:173], v156 offset:1024
	ds_read_b128 v[174:177], v156 offset:2048
	ds_read_b128 v[178:181], v156 offset:3072
	s_add_u32 s36, s30, 0xfff80080
	s_addc_u32 s37, s31, -1
	s_cmp_eq_u32 s52, 28
	s_cselect_b32 s39, s23, s37
	s_cselect_b32 s38, s48, s36
	s_cselect_b32 s37, s21, s51
	s_cselect_b32 s36, s49, s50
	s_add_i32 m0, s17, 0xc000
	ds_read_b128 v[182:185], v157
	ds_read_b128 v[186:189], v157 offset:1024
	ds_read_b128 v[190:193], v157 offset:2048
	ds_read_b128 v[194:197], v157 offset:3072
	ds_read_b128 v[198:201], v157 offset:4096
	ds_read_b128 v[202:205], v157 offset:5120
	ds_read_b128 v[206:209], v157 offset:6144
	ds_read_b128 v[210:213], v157 offset:7168
	global_load_lds_dwordx4 v136, s[30:31]
	s_add_i32 m0, s17, 0xe000
	s_nop 0
	global_load_lds_dwordx4 v138, s[30:31]
	s_waitcnt vmcnt(8) lgkmcnt(0)
	s_setprio 1
	s_barrier
	v_mfma_i32_16x16x64_i8 v[124:127], v[144:147], v[182:185], v[124:127]
	v_mfma_i32_16x16x64_i8 v[116:119], v[158:161], v[182:185], v[116:119]
	v_mfma_i32_16x16x64_i8 v[108:111], v[144:147], v[190:193], v[108:111]
	v_mfma_i32_16x16x64_i8 v[100:103], v[158:161], v[190:193], v[100:103]
	v_mfma_i32_16x16x64_i8 v[92:95], v[144:147], v[198:201], v[92:95]
	v_mfma_i32_16x16x64_i8 v[84:87], v[158:161], v[198:201], v[84:87]
	v_mfma_i32_16x16x64_i8 v[76:79], v[144:147], v[206:209], v[76:79]
	v_mfma_i32_16x16x64_i8 v[68:71], v[158:161], v[206:209], v[68:71]
	v_mfma_i32_16x16x64_i8 v[124:127], v[148:151], v[186:189], v[124:127]
	v_mfma_i32_16x16x64_i8 v[116:119], v[162:165], v[186:189], v[116:119]
	v_mfma_i32_16x16x64_i8 v[108:111], v[148:151], v[194:197], v[108:111]
	v_mfma_i32_16x16x64_i8 v[100:103], v[162:165], v[194:197], v[100:103]
	v_mfma_i32_16x16x64_i8 v[92:95], v[148:151], v[202:205], v[92:95]
	v_mfma_i32_16x16x64_i8 v[84:87], v[162:165], v[202:205], v[84:87]
	v_mfma_i32_16x16x64_i8 v[76:79], v[148:151], v[210:213], v[76:79]
	v_mfma_i32_16x16x64_i8 v[68:71], v[162:165], v[210:213], v[68:71]
	v_mfma_i32_16x16x64_i8 v[120:123], v[166:169], v[182:185], v[120:123]
	v_mfma_i32_16x16x64_i8 v[112:115], v[174:177], v[182:185], v[112:115]
	v_mfma_i32_16x16x64_i8 v[104:107], v[166:169], v[190:193], v[104:107]
	v_mfma_i32_16x16x64_i8 v[96:99], v[174:177], v[190:193], v[96:99]
	v_mfma_i32_16x16x64_i8 v[88:91], v[166:169], v[198:201], v[88:91]
	v_mfma_i32_16x16x64_i8 v[80:83], v[174:177], v[198:201], v[80:83]
	v_mfma_i32_16x16x64_i8 v[72:75], v[166:169], v[206:209], v[72:75]
	v_mfma_i32_16x16x64_i8 v[64:67], v[174:177], v[206:209], v[64:67]
	v_mfma_i32_16x16x64_i8 v[120:123], v[170:173], v[186:189], v[120:123]
	v_mfma_i32_16x16x64_i8 v[112:115], v[178:181], v[186:189], v[112:115]
	v_mfma_i32_16x16x64_i8 v[104:107], v[170:173], v[194:197], v[104:107]
	v_mfma_i32_16x16x64_i8 v[96:99], v[178:181], v[194:197], v[96:99]
	v_mfma_i32_16x16x64_i8 v[88:91], v[170:173], v[202:205], v[88:91]
	v_mfma_i32_16x16x64_i8 v[80:83], v[178:181], v[202:205], v[80:83]
	v_mfma_i32_16x16x64_i8 v[72:75], v[170:173], v[210:213], v[72:75]
	v_mfma_i32_16x16x64_i8 v[64:67], v[178:181], v[210:213], v[64:67]
	s_barrier
	s_setprio 0
	s_add_i32 s53, s44, s2
	s_mov_b32 m0, s53
	ds_read_b128 v[182:185], v157 offset:16384
	ds_read_b128 v[186:189], v157 offset:17408
	ds_read_b128 v[190:193], v157 offset:18432
	ds_read_b128 v[194:197], v157 offset:19456
	ds_read_b128 v[198:201], v157 offset:20480
	ds_read_b128 v[202:205], v157 offset:21504
	ds_read_b128 v[206:209], v157 offset:22528
	ds_read_b128 v[210:213], v157 offset:23552
	global_load_lds_dwordx4 v132, s[36:37]
	s_add_i32 m0, s53, 0x2000
	s_add_u32 s54, s36, 0x80000
	s_mov_b64 s[98:99], s[36:37]
	s_addc_u32 s55, s37, 0
	s_add_i32 s53, s45, s2
	global_load_lds_dwordx4 v128, s[98:99]
	s_mov_b32 m0, s53
	s_mov_b64 s[100:101], s[38:39]
	global_load_lds_dwordx4 v132, s[54:55]
	s_add_i32 m0, s53, 0x2000
	s_nop 0
	global_load_lds_dwordx4 v128, s[54:55]
	s_mov_b64 s[100:101], s[38:39]
	s_mov_b32 m0, s17
	s_nop 0
	global_load_lds_dwordx4 v134, s[100:101]
	s_mov_b32 m0, s29
	s_nop 0
	global_load_lds_dwordx4 v130, s[100:101]
	s_waitcnt vmcnt(8) lgkmcnt(0)
	s_setprio 1
	s_barrier
	v_mfma_i32_16x16x64_i8 v[60:63], v[144:147], v[182:185], v[60:63]
	v_mfma_i32_16x16x64_i8 v[52:55], v[158:161], v[182:185], v[52:55]
	v_mfma_i32_16x16x64_i8 v[44:47], v[144:147], v[190:193], v[44:47]
	v_mfma_i32_16x16x64_i8 v[36:39], v[158:161], v[190:193], v[36:39]
	v_mfma_i32_16x16x64_i8 v[28:31], v[144:147], v[198:201], v[28:31]
	v_mfma_i32_16x16x64_i8 v[20:23], v[158:161], v[198:201], v[20:23]
	v_mfma_i32_16x16x64_i8 v[12:15], v[144:147], v[206:209], v[12:15]
	v_mfma_i32_16x16x64_i8 v[4:7], v[158:161], v[206:209], v[4:7]
	v_mfma_i32_16x16x64_i8 v[60:63], v[148:151], v[186:189], v[60:63]
	v_mfma_i32_16x16x64_i8 v[52:55], v[162:165], v[186:189], v[52:55]
	v_mfma_i32_16x16x64_i8 v[44:47], v[148:151], v[194:197], v[44:47]
	v_mfma_i32_16x16x64_i8 v[36:39], v[162:165], v[194:197], v[36:39]
	v_mfma_i32_16x16x64_i8 v[28:31], v[148:151], v[202:205], v[28:31]
	v_mfma_i32_16x16x64_i8 v[20:23], v[162:165], v[202:205], v[20:23]
	v_mfma_i32_16x16x64_i8 v[12:15], v[148:151], v[210:213], v[12:15]
	v_mfma_i32_16x16x64_i8 v[4:7], v[162:165], v[210:213], v[4:7]
	v_mfma_i32_16x16x64_i8 v[56:59], v[166:169], v[182:185], v[56:59]
	v_mfma_i32_16x16x64_i8 v[48:51], v[174:177], v[182:185], v[48:51]
	v_mfma_i32_16x16x64_i8 v[40:43], v[166:169], v[190:193], v[40:43]
	v_mfma_i32_16x16x64_i8 v[32:35], v[174:177], v[190:193], v[32:35]
	v_mfma_i32_16x16x64_i8 v[24:27], v[166:169], v[198:201], v[24:27]
	v_mfma_i32_16x16x64_i8 v[16:19], v[174:177], v[198:201], v[16:19]
	v_mfma_i32_16x16x64_i8 v[8:11], v[166:169], v[206:209], v[8:11]
	v_mfma_i32_16x16x64_i8 v[0:3], v[174:177], v[206:209], v[0:3]
	v_mfma_i32_16x16x64_i8 v[56:59], v[170:173], v[186:189], v[56:59]
	v_mfma_i32_16x16x64_i8 v[48:51], v[178:181], v[186:189], v[48:51]
	v_mfma_i32_16x16x64_i8 v[40:43], v[170:173], v[194:197], v[40:43]
	v_mfma_i32_16x16x64_i8 v[32:35], v[178:181], v[194:197], v[32:35]
	v_mfma_i32_16x16x64_i8 v[24:27], v[170:173], v[202:205], v[24:27]
	v_mfma_i32_16x16x64_i8 v[16:19], v[178:181], v[202:205], v[16:19]
	v_mfma_i32_16x16x64_i8 v[8:11], v[170:173], v[210:213], v[8:11]
	v_mfma_i32_16x16x64_i8 v[0:3], v[178:181], v[210:213], v[0:3]
	s_barrier
	s_setprio 0
	s_add_i32 s53, 0, 0x18000
	s_add_i32 s54, 0, 0x1c000
	ds_read_b128 v[144:147], v155 offset:32768
	ds_read_b128 v[148:151], v155 offset:33792
	ds_read_b128 v[158:161], v155 offset:34816
	ds_read_b128 v[162:165], v155 offset:35840
	ds_read_b128 v[166:169], v156 offset:32768
	ds_read_b128 v[170:173], v156 offset:33792
	ds_read_b128 v[174:177], v156 offset:34816
	ds_read_b128 v[178:181], v156 offset:35840
	s_add_u32 s38, s38, 0x80000
	s_addc_u32 s39, s39, 0
	s_mov_b32 m0, s33
	ds_read_b128 v[182:185], v157 offset:32768
	ds_read_b128 v[186:189], v157 offset:33792
	ds_read_b128 v[190:193], v157 offset:34816
	ds_read_b128 v[194:197], v157 offset:35840
	ds_read_b128 v[198:201], v157 offset:36864
	ds_read_b128 v[202:205], v157 offset:37888
	ds_read_b128 v[206:209], v157 offset:38912
	ds_read_b128 v[210:213], v157 offset:39936
	global_load_lds_dwordx4 v134, s[38:39]
	s_mov_b32 m0, s35
	s_nop 0
	global_load_lds_dwordx4 v130, s[38:39]
	s_waitcnt vmcnt(8) lgkmcnt(0)
	s_setprio 1
	s_barrier
	v_mfma_i32_16x16x64_i8 v[124:127], v[144:147], v[182:185], v[124:127]
	v_mfma_i32_16x16x64_i8 v[116:119], v[158:161], v[182:185], v[116:119]
	v_mfma_i32_16x16x64_i8 v[108:111], v[144:147], v[190:193], v[108:111]
	v_mfma_i32_16x16x64_i8 v[100:103], v[158:161], v[190:193], v[100:103]
	v_mfma_i32_16x16x64_i8 v[92:95], v[144:147], v[198:201], v[92:95]
	v_mfma_i32_16x16x64_i8 v[84:87], v[158:161], v[198:201], v[84:87]
	v_mfma_i32_16x16x64_i8 v[76:79], v[144:147], v[206:209], v[76:79]
	v_mfma_i32_16x16x64_i8 v[68:71], v[158:161], v[206:209], v[68:71]
	v_mfma_i32_16x16x64_i8 v[124:127], v[148:151], v[186:189], v[124:127]
	v_mfma_i32_16x16x64_i8 v[116:119], v[162:165], v[186:189], v[116:119]
	v_mfma_i32_16x16x64_i8 v[108:111], v[148:151], v[194:197], v[108:111]
	v_mfma_i32_16x16x64_i8 v[100:103], v[162:165], v[194:197], v[100:103]
	v_mfma_i32_16x16x64_i8 v[92:95], v[148:151], v[202:205], v[92:95]
	v_mfma_i32_16x16x64_i8 v[84:87], v[162:165], v[202:205], v[84:87]
	v_mfma_i32_16x16x64_i8 v[76:79], v[148:151], v[210:213], v[76:79]
	v_mfma_i32_16x16x64_i8 v[68:71], v[162:165], v[210:213], v[68:71]
	v_mfma_i32_16x16x64_i8 v[120:123], v[166:169], v[182:185], v[120:123]
	v_mfma_i32_16x16x64_i8 v[112:115], v[174:177], v[182:185], v[112:115]
	v_mfma_i32_16x16x64_i8 v[104:107], v[166:169], v[190:193], v[104:107]
	v_mfma_i32_16x16x64_i8 v[96:99], v[174:177], v[190:193], v[96:99]
	v_mfma_i32_16x16x64_i8 v[88:91], v[166:169], v[198:201], v[88:91]
	v_mfma_i32_16x16x64_i8 v[80:83], v[174:177], v[198:201], v[80:83]
	v_mfma_i32_16x16x64_i8 v[72:75], v[166:169], v[206:209], v[72:75]
	v_mfma_i32_16x16x64_i8 v[64:67], v[174:177], v[206:209], v[64:67]
	v_mfma_i32_16x16x64_i8 v[120:123], v[170:173], v[186:189], v[120:123]
	v_mfma_i32_16x16x64_i8 v[112:115], v[178:181], v[186:189], v[112:115]
	v_mfma_i32_16x16x64_i8 v[104:107], v[170:173], v[194:197], v[104:107]
	v_mfma_i32_16x16x64_i8 v[96:99], v[178:181], v[194:197], v[96:99]
	v_mfma_i32_16x16x64_i8 v[88:91], v[170:173], v[202:205], v[88:91]
	v_mfma_i32_16x16x64_i8 v[80:83], v[178:181], v[202:205], v[80:83]
	v_mfma_i32_16x16x64_i8 v[72:75], v[170:173], v[210:213], v[72:75]
	v_mfma_i32_16x16x64_i8 v[64:67], v[178:181], v[210:213], v[64:67]
	s_barrier
	s_setprio 0
	s_add_i32 s38, s53, s2
	s_add_i32 m0, s38, -128
	ds_read_b128 v[182:185], v157 offset:49152
	ds_read_b128 v[186:189], v157 offset:50176
	ds_read_b128 v[190:193], v157 offset:51200
	ds_read_b128 v[194:197], v157 offset:52224
	ds_read_b128 v[198:201], v157 offset:53248
	ds_read_b128 v[202:205], v157 offset:54272
	ds_read_b128 v[206:209], v157 offset:55296
	ds_read_b128 v[210:213], v157 offset:56320
	global_load_lds_dwordx4 v132, s[36:37] offset:128
	s_add_i32 m0, s38, 8064
	s_add_u32 s36, s36, 0x80080
	s_addc_u32 s37, s37, 0
	s_add_i32 s38, s54, s2
	global_load_lds_dwordx4 v128, s[98:99] offset:128
	s_mov_b32 m0, s38
	s_nop 0
	global_load_lds_dwordx4 v132, s[36:37]
	s_add_i32 m0, s38, 0x2000
	s_nop 0
	global_load_lds_dwordx4 v128, s[36:37]
	s_add_i32 m0, s42, -128
	s_nop 0
	global_load_lds_dwordx4 v134, s[100:101] offset:128
	s_add_i32 m0, s43, -128
	s_nop 0
	global_load_lds_dwordx4 v130, s[100:101] offset:128
	s_waitcnt vmcnt(8) lgkmcnt(0)
	s_setprio 1
	s_barrier
	v_mfma_i32_16x16x64_i8 v[60:63], v[144:147], v[182:185], v[60:63]
	v_mfma_i32_16x16x64_i8 v[52:55], v[158:161], v[182:185], v[52:55]
	v_mfma_i32_16x16x64_i8 v[44:47], v[144:147], v[190:193], v[44:47]
	v_mfma_i32_16x16x64_i8 v[36:39], v[158:161], v[190:193], v[36:39]
	v_mfma_i32_16x16x64_i8 v[28:31], v[144:147], v[198:201], v[28:31]
	v_mfma_i32_16x16x64_i8 v[20:23], v[158:161], v[198:201], v[20:23]
	v_mfma_i32_16x16x64_i8 v[12:15], v[144:147], v[206:209], v[12:15]
	v_mfma_i32_16x16x64_i8 v[4:7], v[158:161], v[206:209], v[4:7]
	v_mfma_i32_16x16x64_i8 v[60:63], v[148:151], v[186:189], v[60:63]
	v_mfma_i32_16x16x64_i8 v[52:55], v[162:165], v[186:189], v[52:55]
	v_mfma_i32_16x16x64_i8 v[44:47], v[148:151], v[194:197], v[44:47]
	v_mfma_i32_16x16x64_i8 v[36:39], v[162:165], v[194:197], v[36:39]
	v_mfma_i32_16x16x64_i8 v[28:31], v[148:151], v[202:205], v[28:31]
	v_mfma_i32_16x16x64_i8 v[20:23], v[162:165], v[202:205], v[20:23]
	v_mfma_i32_16x16x64_i8 v[12:15], v[148:151], v[210:213], v[12:15]
	v_mfma_i32_16x16x64_i8 v[4:7], v[162:165], v[210:213], v[4:7]
	v_mfma_i32_16x16x64_i8 v[56:59], v[166:169], v[182:185], v[56:59]
	v_mfma_i32_16x16x64_i8 v[48:51], v[174:177], v[182:185], v[48:51]
	v_mfma_i32_16x16x64_i8 v[40:43], v[166:169], v[190:193], v[40:43]
	v_mfma_i32_16x16x64_i8 v[32:35], v[174:177], v[190:193], v[32:35]
	v_mfma_i32_16x16x64_i8 v[24:27], v[166:169], v[198:201], v[24:27]
	v_mfma_i32_16x16x64_i8 v[16:19], v[174:177], v[198:201], v[16:19]
	v_mfma_i32_16x16x64_i8 v[8:11], v[166:169], v[206:209], v[8:11]
	v_mfma_i32_16x16x64_i8 v[0:3], v[174:177], v[206:209], v[0:3]
	v_mfma_i32_16x16x64_i8 v[56:59], v[170:173], v[186:189], v[56:59]
	v_mfma_i32_16x16x64_i8 v[48:51], v[178:181], v[186:189], v[48:51]
	v_mfma_i32_16x16x64_i8 v[40:43], v[170:173], v[194:197], v[40:43]
	v_mfma_i32_16x16x64_i8 v[32:35], v[178:181], v[194:197], v[32:35]
	v_mfma_i32_16x16x64_i8 v[24:27], v[170:173], v[202:205], v[24:27]
	v_mfma_i32_16x16x64_i8 v[16:19], v[178:181], v[202:205], v[16:19]
	v_mfma_i32_16x16x64_i8 v[8:11], v[170:173], v[210:213], v[8:11]
	v_mfma_i32_16x16x64_i8 v[0:3], v[178:181], v[210:213], v[0:3]
	s_barrier
	s_setprio 0
	s_add_i32 s52, s52, 2
	s_add_u32 s30, s30, 0x100
	s_addc_u32 s31, s31, 0
	s_add_u32 s50, s50, 0x100
	s_addc_u32 s51, s51, 0
	s_cmp_gt_u32 s52, 29
	s_cbranch_scc0 .LBB0_773
	s_and_b64 vcc, exec, s[14:15]
	s_cbranch_vccz .LBB0_776
	s_barrier

.LBB0_858:
	ds_read_b128 v[152:155], v149
	ds_read_b128 v[156:159], v149 offset:1024
	ds_read_b128 v[160:163], v149 offset:2048
	ds_read_b128 v[164:167], v149 offset:3072
	ds_read_b128 v[168:171], v150
	ds_read_b128 v[172:175], v150 offset:1024
	ds_read_b128 v[176:179], v150 offset:2048
	ds_read_b128 v[180:183], v150 offset:3072
	s_add_u32 s26, s24, 0x100
	s_addc_u32 s27, s25, 0
	s_cmpk_eq_i32 s54, 0xa8
	s_cselect_b32 s31, s5, s27
	s_cselect_b32 s30, s4, s26
	s_cselect_b32 s29, s23, s53
	s_cselect_b32 s28, s22, s52
	s_add_i32 m0, s33, 0xc000
	ds_read_b128 v[184:187], v151
	ds_read_b128 v[188:191], v151 offset:1024
	ds_read_b128 v[192:195], v151 offset:2048
	ds_read_b128 v[196:199], v151 offset:3072
	ds_read_b128 v[200:203], v151 offset:4096
	ds_read_b128 v[204:207], v151 offset:5120
	ds_read_b128 v[208:211], v151 offset:6144
	ds_read_b128 v[212:215], v151 offset:7168
	global_load_lds_dwordx4 v136, s[24:25]
	s_add_i32 m0, s33, 0xe000
	s_nop 0
	global_load_lds_dwordx4 v138, s[24:25]
	s_waitcnt vmcnt(8) lgkmcnt(0)
	s_setprio 1
	s_barrier
	v_mfma_f32_16x16x32_bf16 v[124:127], v[152:155], v[184:187], v[124:127]
	v_mfma_f32_16x16x32_bf16 v[120:123], v[160:163], v[184:187], v[120:123]
	v_mfma_f32_16x16x32_bf16 v[116:119], v[152:155], v[192:195], v[116:119]
	v_mfma_f32_16x16x32_bf16 v[108:111], v[160:163], v[192:195], v[108:111]
	v_mfma_f32_16x16x32_bf16 v[100:103], v[152:155], v[200:203], v[100:103]
	v_mfma_f32_16x16x32_bf16 v[92:95], v[160:163], v[200:203], v[92:95]
	v_mfma_f32_16x16x32_bf16 v[84:87], v[152:155], v[208:211], v[84:87]
	v_mfma_f32_16x16x32_bf16 v[76:79], v[160:163], v[208:211], v[76:79]
	v_mfma_f32_16x16x32_bf16 v[124:127], v[156:159], v[188:191], v[124:127]
	v_mfma_f32_16x16x32_bf16 v[120:123], v[164:167], v[188:191], v[120:123]
	v_mfma_f32_16x16x32_bf16 v[116:119], v[156:159], v[196:199], v[116:119]
	v_mfma_f32_16x16x32_bf16 v[108:111], v[164:167], v[196:199], v[108:111]
	v_mfma_f32_16x16x32_bf16 v[100:103], v[156:159], v[204:207], v[100:103]
	v_mfma_f32_16x16x32_bf16 v[92:95], v[164:167], v[204:207], v[92:95]
	v_mfma_f32_16x16x32_bf16 v[84:87], v[156:159], v[212:215], v[84:87]
	v_mfma_f32_16x16x32_bf16 v[76:79], v[164:167], v[212:215], v[76:79]
	v_mfma_f32_16x16x32_bf16 v[112:115], v[168:171], v[184:187], v[112:115]
	v_mfma_f32_16x16x32_bf16 v[104:107], v[176:179], v[184:187], v[104:107]
	v_mfma_f32_16x16x32_bf16 v[96:99], v[168:171], v[192:195], v[96:99]
	v_mfma_f32_16x16x32_bf16 v[88:91], v[176:179], v[192:195], v[88:91]
	v_mfma_f32_16x16x32_bf16 v[80:83], v[168:171], v[200:203], v[80:83]
	v_mfma_f32_16x16x32_bf16 v[72:75], v[176:179], v[200:203], v[72:75]
	v_mfma_f32_16x16x32_bf16 v[68:71], v[168:171], v[208:211], v[68:71]
	v_mfma_f32_16x16x32_bf16 v[64:67], v[176:179], v[208:211], v[64:67]
	v_mfma_f32_16x16x32_bf16 v[112:115], v[172:175], v[188:191], v[112:115]
	v_mfma_f32_16x16x32_bf16 v[104:107], v[180:183], v[188:191], v[104:107]
	v_mfma_f32_16x16x32_bf16 v[96:99], v[172:175], v[196:199], v[96:99]
	v_mfma_f32_16x16x32_bf16 v[88:91], v[180:183], v[196:199], v[88:91]
	v_mfma_f32_16x16x32_bf16 v[80:83], v[172:175], v[204:207], v[80:83]
	v_mfma_f32_16x16x32_bf16 v[72:75], v[180:183], v[204:207], v[72:75]
	v_mfma_f32_16x16x32_bf16 v[68:71], v[172:175], v[212:215], v[68:71]
	v_mfma_f32_16x16x32_bf16 v[64:67], v[180:183], v[212:215], v[64:67]
	s_barrier
	s_setprio 0
	s_add_i32 s24, s42, s2
	s_mov_b32 m0, s24
	ds_read_b128 v[184:187], v151 offset:16384
	ds_read_b128 v[188:191], v151 offset:17408
	ds_read_b128 v[192:195], v151 offset:18432
	ds_read_b128 v[196:199], v151 offset:19456
	ds_read_b128 v[200:203], v151 offset:20480
	ds_read_b128 v[204:207], v151 offset:21504
	ds_read_b128 v[208:211], v151 offset:22528
	ds_read_b128 v[212:215], v151 offset:23552
	global_load_lds_dwordx4 v132, s[28:29]
	s_add_i32 m0, s24, 0x2000
	s_add_u32 s24, s28, 0x2b0000
	s_mov_b64 s[98:99], s[28:29]
	s_addc_u32 s25, s29, 0
	s_add_i32 s55, s43, s2
	global_load_lds_dwordx4 v128, s[98:99]
	s_mov_b32 m0, s55
	s_nop 0
	global_load_lds_dwordx4 v132, s[24:25]
	s_add_i32 m0, s55, 0x2000
	s_nop 0
	global_load_lds_dwordx4 v128, s[24:25]
	s_mov_b32 m0, s33
	s_nop 0
	global_load_lds_dwordx4 v134, s[30:31]
	s_mov_b32 m0, s35
	s_nop 0
	global_load_lds_dwordx4 v130, s[30:31]
	s_waitcnt vmcnt(8) lgkmcnt(0)
	s_setprio 1
	s_barrier
	v_mfma_f32_16x16x32_bf16 v[60:63], v[152:155], v[184:187], v[60:63]
	v_mfma_f32_16x16x32_bf16 v[56:59], v[160:163], v[184:187], v[56:59]
	v_mfma_f32_16x16x32_bf16 v[52:55], v[152:155], v[192:195], v[52:55]
	v_mfma_f32_16x16x32_bf16 v[44:47], v[160:163], v[192:195], v[44:47]
	v_mfma_f32_16x16x32_bf16 v[36:39], v[152:155], v[200:203], v[36:39]
	v_mfma_f32_16x16x32_bf16 v[28:31], v[160:163], v[200:203], v[28:31]
	v_mfma_f32_16x16x32_bf16 v[20:23], v[152:155], v[208:211], v[20:23]
	v_mfma_f32_16x16x32_bf16 v[12:15], v[160:163], v[208:211], v[12:15]
	v_mfma_f32_16x16x32_bf16 v[60:63], v[156:159], v[188:191], v[60:63]
	v_mfma_f32_16x16x32_bf16 v[56:59], v[164:167], v[188:191], v[56:59]
	v_mfma_f32_16x16x32_bf16 v[52:55], v[156:159], v[196:199], v[52:55]
	v_mfma_f32_16x16x32_bf16 v[44:47], v[164:167], v[196:199], v[44:47]
	v_mfma_f32_16x16x32_bf16 v[36:39], v[156:159], v[204:207], v[36:39]
	v_mfma_f32_16x16x32_bf16 v[28:31], v[164:167], v[204:207], v[28:31]
	v_mfma_f32_16x16x32_bf16 v[20:23], v[156:159], v[212:215], v[20:23]
	v_mfma_f32_16x16x32_bf16 v[12:15], v[164:167], v[212:215], v[12:15]
	v_mfma_f32_16x16x32_bf16 v[48:51], v[168:171], v[184:187], v[48:51]
	v_mfma_f32_16x16x32_bf16 v[40:43], v[176:179], v[184:187], v[40:43]
	v_mfma_f32_16x16x32_bf16 v[32:35], v[168:171], v[192:195], v[32:35]
	v_mfma_f32_16x16x32_bf16 v[24:27], v[176:179], v[192:195], v[24:27]
	v_mfma_f32_16x16x32_bf16 v[16:19], v[168:171], v[200:203], v[16:19]
	v_mfma_f32_16x16x32_bf16 v[8:11], v[176:179], v[200:203], v[8:11]
	v_mfma_f32_16x16x32_bf16 v[4:7], v[168:171], v[208:211], v[4:7]
	v_mfma_f32_16x16x32_bf16 v[0:3], v[176:179], v[208:211], v[0:3]
	v_mfma_f32_16x16x32_bf16 v[48:51], v[172:175], v[188:191], v[48:51]
	v_mfma_f32_16x16x32_bf16 v[40:43], v[180:183], v[188:191], v[40:43]
	v_mfma_f32_16x16x32_bf16 v[32:35], v[172:175], v[196:199], v[32:35]
	v_mfma_f32_16x16x32_bf16 v[24:27], v[180:183], v[196:199], v[24:27]
	v_mfma_f32_16x16x32_bf16 v[16:19], v[172:175], v[204:207], v[16:19]
	v_mfma_f32_16x16x32_bf16 v[8:11], v[180:183], v[204:207], v[8:11]
	v_mfma_f32_16x16x32_bf16 v[4:7], v[172:175], v[212:215], v[4:7]
	v_mfma_f32_16x16x32_bf16 v[0:3], v[180:183], v[212:215], v[0:3]
	s_barrier
	s_setprio 0
	s_add_i32 s55, 0, 0x18000
	s_add_i32 s58, 0, 0x1c000
	ds_read_b128 v[152:155], v149 offset:32768
	ds_read_b128 v[156:159], v149 offset:33792
	ds_read_b128 v[160:163], v149 offset:34816
	ds_read_b128 v[164:167], v149 offset:35840
	ds_read_b128 v[168:171], v150 offset:32768
	ds_read_b128 v[172:175], v150 offset:33792
	ds_read_b128 v[176:179], v150 offset:34816
	ds_read_b128 v[180:183], v150 offset:35840
	s_add_u32 s24, s30, 0x2b0000
	s_addc_u32 s25, s31, 0
	s_mov_b32 m0, s36
	ds_read_b128 v[184:187], v151 offset:32768
	ds_read_b128 v[188:191], v151 offset:33792
	ds_read_b128 v[192:195], v151 offset:34816
	ds_read_b128 v[196:199], v151 offset:35840
	ds_read_b128 v[200:203], v151 offset:36864
	ds_read_b128 v[204:207], v151 offset:37888
	ds_read_b128 v[208:211], v151 offset:38912
	ds_read_b128 v[212:215], v151 offset:39936
	global_load_lds_dwordx4 v134, s[24:25]
	s_mov_b32 m0, s37
	s_nop 0
	global_load_lds_dwordx4 v130, s[24:25]
	s_waitcnt vmcnt(8) lgkmcnt(0)
	s_setprio 1
	s_barrier
	v_mfma_f32_16x16x32_bf16 v[124:127], v[152:155], v[184:187], v[124:127]
	v_mfma_f32_16x16x32_bf16 v[120:123], v[160:163], v[184:187], v[120:123]
	v_mfma_f32_16x16x32_bf16 v[116:119], v[152:155], v[192:195], v[116:119]
	v_mfma_f32_16x16x32_bf16 v[108:111], v[160:163], v[192:195], v[108:111]
	v_mfma_f32_16x16x32_bf16 v[100:103], v[152:155], v[200:203], v[100:103]
	v_mfma_f32_16x16x32_bf16 v[92:95], v[160:163], v[200:203], v[92:95]
	v_mfma_f32_16x16x32_bf16 v[84:87], v[152:155], v[208:211], v[84:87]
	v_mfma_f32_16x16x32_bf16 v[76:79], v[160:163], v[208:211], v[76:79]
	v_mfma_f32_16x16x32_bf16 v[124:127], v[156:159], v[188:191], v[124:127]
	v_mfma_f32_16x16x32_bf16 v[120:123], v[164:167], v[188:191], v[120:123]
	v_mfma_f32_16x16x32_bf16 v[116:119], v[156:159], v[196:199], v[116:119]
	v_mfma_f32_16x16x32_bf16 v[108:111], v[164:167], v[196:199], v[108:111]
	v_mfma_f32_16x16x32_bf16 v[100:103], v[156:159], v[204:207], v[100:103]
	v_mfma_f32_16x16x32_bf16 v[92:95], v[164:167], v[204:207], v[92:95]
	v_mfma_f32_16x16x32_bf16 v[84:87], v[156:159], v[212:215], v[84:87]
	v_mfma_f32_16x16x32_bf16 v[76:79], v[164:167], v[212:215], v[76:79]
	v_mfma_f32_16x16x32_bf16 v[112:115], v[168:171], v[184:187], v[112:115]
	v_mfma_f32_16x16x32_bf16 v[104:107], v[176:179], v[184:187], v[104:107]
	v_mfma_f32_16x16x32_bf16 v[96:99], v[168:171], v[192:195], v[96:99]
	v_mfma_f32_16x16x32_bf16 v[88:91], v[176:179], v[192:195], v[88:91]
	v_mfma_f32_16x16x32_bf16 v[80:83], v[168:171], v[200:203], v[80:83]
	v_mfma_f32_16x16x32_bf16 v[72:75], v[176:179], v[200:203], v[72:75]
	v_mfma_f32_16x16x32_bf16 v[68:71], v[168:171], v[208:211], v[68:71]
	v_mfma_f32_16x16x32_bf16 v[64:67], v[176:179], v[208:211], v[64:67]
	v_mfma_f32_16x16x32_bf16 v[112:115], v[172:175], v[188:191], v[112:115]
	v_mfma_f32_16x16x32_bf16 v[104:107], v[180:183], v[188:191], v[104:107]
	v_mfma_f32_16x16x32_bf16 v[96:99], v[172:175], v[196:199], v[96:99]
	v_mfma_f32_16x16x32_bf16 v[88:91], v[180:183], v[196:199], v[88:91]
	v_mfma_f32_16x16x32_bf16 v[80:83], v[172:175], v[204:207], v[80:83]
	v_mfma_f32_16x16x32_bf16 v[72:75], v[180:183], v[204:207], v[72:75]
	v_mfma_f32_16x16x32_bf16 v[68:71], v[172:175], v[212:215], v[68:71]
	v_mfma_f32_16x16x32_bf16 v[64:67], v[180:183], v[212:215], v[64:67]
	s_barrier
	s_setprio 0
	s_add_i32 s24, s55, s2
	s_add_i32 m0, s24, -128
	ds_read_b128 v[184:187], v151 offset:49152
	ds_read_b128 v[188:191], v151 offset:50176
	ds_read_b128 v[192:195], v151 offset:51200
	ds_read_b128 v[196:199], v151 offset:52224
	ds_read_b128 v[200:203], v151 offset:53248
	ds_read_b128 v[204:207], v151 offset:54272
	ds_read_b128 v[208:211], v151 offset:55296
	ds_read_b128 v[212:215], v151 offset:56320
	global_load_lds_dwordx4 v132, s[28:29] offset:128
	s_add_i32 m0, s24, 8064
	s_add_u32 s24, s28, 0x2b0080
	s_addc_u32 s25, s29, 0
	s_add_i32 s28, s58, s2
	global_load_lds_dwordx4 v128, s[98:99] offset:128
	s_mov_b32 m0, s28
	s_nop 0
	global_load_lds_dwordx4 v132, s[24:25]
	s_add_i32 m0, s28, 0x2000
	s_nop 0
	global_load_lds_dwordx4 v128, s[24:25]
	s_add_i32 m0, s40, -128
	s_nop 0
	global_load_lds_dwordx4 v134, s[30:31] offset:128
	s_add_i32 m0, s41, -128
	s_nop 0
	global_load_lds_dwordx4 v130, s[30:31] offset:128
	s_waitcnt vmcnt(8) lgkmcnt(0)
	s_setprio 1
	s_barrier
	v_mfma_f32_16x16x32_bf16 v[60:63], v[152:155], v[184:187], v[60:63]
	v_mfma_f32_16x16x32_bf16 v[56:59], v[160:163], v[184:187], v[56:59]
	v_mfma_f32_16x16x32_bf16 v[52:55], v[152:155], v[192:195], v[52:55]
	v_mfma_f32_16x16x32_bf16 v[44:47], v[160:163], v[192:195], v[44:47]
	v_mfma_f32_16x16x32_bf16 v[36:39], v[152:155], v[200:203], v[36:39]
	v_mfma_f32_16x16x32_bf16 v[28:31], v[160:163], v[200:203], v[28:31]
	v_mfma_f32_16x16x32_bf16 v[20:23], v[152:155], v[208:211], v[20:23]
	v_mfma_f32_16x16x32_bf16 v[12:15], v[160:163], v[208:211], v[12:15]
	v_mfma_f32_16x16x32_bf16 v[60:63], v[156:159], v[188:191], v[60:63]
	v_mfma_f32_16x16x32_bf16 v[56:59], v[164:167], v[188:191], v[56:59]
	v_mfma_f32_16x16x32_bf16 v[52:55], v[156:159], v[196:199], v[52:55]
	v_mfma_f32_16x16x32_bf16 v[44:47], v[164:167], v[196:199], v[44:47]
	v_mfma_f32_16x16x32_bf16 v[36:39], v[156:159], v[204:207], v[36:39]
	v_mfma_f32_16x16x32_bf16 v[28:31], v[164:167], v[204:207], v[28:31]
	v_mfma_f32_16x16x32_bf16 v[20:23], v[156:159], v[212:215], v[20:23]
	v_mfma_f32_16x16x32_bf16 v[12:15], v[164:167], v[212:215], v[12:15]
	v_mfma_f32_16x16x32_bf16 v[48:51], v[168:171], v[184:187], v[48:51]
	v_mfma_f32_16x16x32_bf16 v[40:43], v[176:179], v[184:187], v[40:43]
	v_mfma_f32_16x16x32_bf16 v[32:35], v[168:171], v[192:195], v[32:35]
	v_mfma_f32_16x16x32_bf16 v[24:27], v[176:179], v[192:195], v[24:27]
	v_mfma_f32_16x16x32_bf16 v[16:19], v[168:171], v[200:203], v[16:19]
	v_mfma_f32_16x16x32_bf16 v[8:11], v[176:179], v[200:203], v[8:11]
	v_mfma_f32_16x16x32_bf16 v[4:7], v[168:171], v[208:211], v[4:7]
	v_mfma_f32_16x16x32_bf16 v[0:3], v[176:179], v[208:211], v[0:3]
	v_mfma_f32_16x16x32_bf16 v[48:51], v[172:175], v[188:191], v[48:51]
	v_mfma_f32_16x16x32_bf16 v[40:43], v[180:183], v[188:191], v[40:43]
	v_mfma_f32_16x16x32_bf16 v[32:35], v[172:175], v[196:199], v[32:35]
	v_mfma_f32_16x16x32_bf16 v[24:27], v[180:183], v[196:199], v[24:27]
	v_mfma_f32_16x16x32_bf16 v[16:19], v[172:175], v[204:207], v[16:19]
	v_mfma_f32_16x16x32_bf16 v[8:11], v[180:183], v[204:207], v[8:11]
	v_mfma_f32_16x16x32_bf16 v[4:7], v[172:175], v[212:215], v[4:7]
	v_mfma_f32_16x16x32_bf16 v[0:3], v[180:183], v[212:215], v[0:3]
	s_barrier
	s_setprio 0
	s_add_i32 s54, s54, 2
	s_add_u32 s52, s52, 0x100
	s_addc_u32 s53, s53, 0
	s_cmpk_gt_u32 s54, 0xa9
	s_mov_b64 s[24:25], s[26:27]
	s_cbranch_scc0 .LBB0_858
	s_and_b64 vcc, exec, s[10:11]
	s_cbranch_vccz .LBB0_861
	s_barrier
